# v074 + ssm step 3: waves 4-7 start half a block late (one s_sleep 30) so SIMD partners alternate fragment-load waits with gelu/MFMA work
# speedup vs baseline: 1.0170x; 1.0170x over previous
; __device__ __forceinline__ unsigned cvtpk(float lo, float hi) { f32x2_t v = {lo, hi}; bf16x2_t b = __builtin_convertvector(v, bf16x2_t); return __builtin_bit_cast(unsigned, b); }
; __device__ __forceinline__ unsigned f2bf(float f) { return cvtpk(f, 0.f); }
; __device__ __forceinline__ float gelu_tanh(float x) { const float u = 0.7978845608028654f * (x + 0.044715f * x * x * x); const float th = 1.0f - 2.0f * __builtin_amdgcn_rcpf(__expf(2.0f * u) + 1.0f); return 0.5f * x * (1.0f + th); }
; __device__ __forceinline__ int crow16(int g, int hh) { return (g & 3) + 8 * (g >> 2) + 4 * hh; }
; __device__ __forceinline__ void ssm_v2(const KA& A, const Ctx& F, int l, int b, int g) {
;     ...
;     bf16x8_t xf[8];
;     { const float* zp = ZF + (32 * w + r32) * ZS + 8 * hh;
; #pragma unroll
;       for (int s = 0; s < 8; ++s) { const f32x4 a0 = *(const f32x4*)(zp + 16 * s), a1 = *(const f32x4*)(zp + 16 * s + 4);
;           v4u pw; pw.x = cvtpk(a0[0], a0[1]); pw.y = cvtpk(a0[2], a0[3]); pw.z = cvtpk(a1[0], a1[1]); pw.w = cvtpk(a1[2], a1[3]); xf[s] = __builtin_bit_cast(bf16x8_t, pw); } }
; #pragma unroll
;     for (int nt = 0; nt < 8; ++nt) if (sp_ & 4) {
;         f32x16 acc = {};
;         const bf16* tp = TM + (size_t)(nt * 16 * 64 + lane) * 8; const bf16* hp = HM + (size_t)(nt * 8 * 64 + lane) * 8;
;         { bf16x8_t tf[16], hf[8];
; #pragma unroll
;           for (int s = 0; s < 16; ++s) if (s <= 2 * nt + 1) tf[s] = *(const bf16x8_t*)(tp + s * 512);
; #pragma unroll
;           for (int s = 0; s < 8; ++s) hf[s] = *(const bf16x8_t*)(hp + s * 512);
; #pragma unroll
;           for (int s = 0; s < 16; ++s) if (s <= 2 * nt + 1) asm volatile("" :: "v"(tf[s]));
;           asm volatile("" :: "v"(hf[0]), "v"(hf[1]), "v"(hf[2]), "v"(hf[3]), "v"(hf[4]), "v"(hf[5]), "v"(hf[6]), "v"(hf[7]));
; #pragma unroll
;           for (int s = 0; s < 16; ++s) if (s <= 2 * nt + 1) acc = __builtin_amdgcn_mfma_f32_32x32x16_bf16(uf[s], tf[s], acc, 0, 0, 0);
; #pragma unroll
;           for (int s = 0; s < 8; ++s) acc = __builtin_amdgcn_mfma_f32_32x32x16_bf16(xf[s], hf[s], acc, 0, 0, 0); }
;         bf16* op = PS + (tok0 + 2 * nt + (r32 >> 4)) * PSW + C_SSM + 16 * g + (r32 & 15);
; #pragma unroll
;         for (int q = 0; q < 16; ++q) { const bf16 gv_ = (bf16)f2bf(gelu_tanh(acc[q])); if (!(F.dry && (DRY_SEL & 2))) op[(size_t)(16 * crow16(q, hh)) * PSW] = gv_; }
;     }
.LBB0_180:
	v_lshlrev_b64 v[0:1], 4, v[114:115]
	v_lshl_add_u64 v[2:3], s[4:5], 0, v[0:1]
	s_waitcnt lgkmcnt(0)
	s_barrier
	global_load_dwordx4 v[124:127], v[2:3], off
	global_load_dwordx4 v[132:135], v[2:3], off offset:1024
	s_add_u32 s2, s4, 0x30000
	s_addc_u32 s3, s5, 0
	v_lshl_add_u64 v[0:1], s[2:3], 0, v[0:1]
	global_load_dwordx4 v[136:139], v[0:1], off
	global_load_dwordx4 v[140:143], v[0:1], off offset:1024
	global_load_dwordx4 v[144:147], v[0:1], off offset:2048
	global_load_dwordx4 v[148:151], v[0:1], off offset:3072
	v_add_co_u32_e32 v0, vcc, s66, v0
	v_lshl_or_b32 v2, s6, 5, v85
	s_nop 0
	v_addc_co_u32_e32 v1, vcc, 0, v1, vcc
	global_load_dwordx4 v[152:155], v[0:1], off
	global_load_dwordx4 v[156:159], v[0:1], off offset:1024
	global_load_dwordx4 v[160:163], v[0:1], off offset:2048
	global_load_dwordx4 v[164:167], v[0:1], off offset:3072
	s_cmp_lt_u32 s6, 4
	s_cbranch_scc1 .Lssm_nostag
	s_sleep 30
.Lssm_nostag:
	s_movk_i32 s0, 0x210
	v_lshlrev_b32_e32 v3, 2, v86
	v_lshrrev_b32_e32 v4, 4, v85
	v_and_b32_e32 v5, 15, v130
	v_mul_lo_u32 v2, v2, s0
	v_or_b32_e32 v115, s8, v4
	v_lshlrev_b32_e32 v120, 1, v5
	v_add3_u32 v128, 0, v2, v3
	v_mul_u32_u24_e32 v118, 0x58000, v84
	ds_read_b128 v[82:85], v128
	ds_read_b128 v[86:89], v128 offset:16
	ds_read_b128 v[90:93], v128 offset:64
	ds_read_b128 v[94:97], v128 offset:80
	ds_read_b128 v[98:101], v128 offset:128
	ds_read_b128 v[102:105], v128 offset:144
	ds_read_b128 v[106:109], v128 offset:192
	ds_read_b128 v[110:113], v128 offset:208
	ds_read_b128 v[168:171], v128 offset:256
	ds_read_b128 v[172:175], v128 offset:272
	s_waitcnt lgkmcnt(9)
	v_cvt_pk_bf16_f32 v82, v82, v83
	v_cvt_pk_bf16_f32 v83, v84, v85
	s_waitcnt lgkmcnt(8)
	v_cvt_pk_bf16_f32 v84, v86, v87
	v_cvt_pk_bf16_f32 v85, v88, v89
	s_waitcnt lgkmcnt(7)
	v_cvt_pk_bf16_f32 v86, v90, v91
	v_cvt_pk_bf16_f32 v87, v92, v93
	s_waitcnt lgkmcnt(6)
	v_cvt_pk_bf16_f32 v88, v94, v95
	v_cvt_pk_bf16_f32 v89, v96, v97
	s_waitcnt lgkmcnt(5)
	v_cvt_pk_bf16_f32 v90, v98, v99
	v_cvt_pk_bf16_f32 v91, v100, v101
	s_waitcnt lgkmcnt(4)
	v_cvt_pk_bf16_f32 v92, v102, v103
	v_cvt_pk_bf16_f32 v93, v104, v105
	v_mov_b64_e32 v[116:117], s[82:83]
	s_lshl_b32 s0, s9, 1
	v_mad_u64_u32 v[122:123], s[8:9], v115, s92, v[116:117]
	s_mov_b32 s1, s24
	v_mad_i32_i24 v123, s7, v236, v123
	v_mov_b32_e32 v121, v81
	v_lshl_add_u64 v[94:95], v[122:123], 0, s[0:1]
	v_lshl_add_u64 v[98:99], v[94:95], 0, v[120:121]
	s_waitcnt lgkmcnt(3)
	v_cvt_pk_bf16_f32 v94, v106, v107
	v_cvt_pk_bf16_f32 v95, v108, v109
	s_waitcnt lgkmcnt(2)
	v_cvt_pk_bf16_f32 v96, v110, v111
	v_cvt_pk_bf16_f32 v97, v112, v113
	v_mov_b32_e32 v119, v81
	v_lshl_add_u64 v[122:123], v[98:99], 0, v[118:119]
	s_waitcnt lgkmcnt(1)
	v_cvt_pk_bf16_f32 v98, v168, v169
	v_cvt_pk_bf16_f32 v99, v170, v171
	s_waitcnt lgkmcnt(0)
	v_cvt_pk_bf16_f32 v100, v172, v173
	v_cvt_pk_bf16_f32 v101, v174, v175
	ds_read_b128 v[176:179], v128 offset:320
	ds_read_b128 v[184:187], v128 offset:336
	ds_read_b128 v[188:191], v128 offset:384
	ds_read_b128 v[192:195], v128 offset:400
	ds_read_b128 v[196:199], v128 offset:448
	ds_read_b128 v[200:203], v128 offset:464
	v_add_co_u32_e32 v128, vcc, s66, v122
	s_waitcnt lgkmcnt(5)
	v_cvt_pk_bf16_f32 v102, v176, v177
	v_cvt_pk_bf16_f32 v103, v178, v179
	s_waitcnt lgkmcnt(4)
	v_cvt_pk_bf16_f32 v104, v184, v185
	v_cvt_pk_bf16_f32 v105, v186, v187
	s_waitcnt lgkmcnt(3)
	v_cvt_pk_bf16_f32 v110, v188, v189
	v_cvt_pk_bf16_f32 v111, v190, v191
	s_waitcnt lgkmcnt(2)
	v_cvt_pk_bf16_f32 v112, v192, v193
	v_cvt_pk_bf16_f32 v113, v194, v195
	s_waitcnt lgkmcnt(1)
	v_cvt_pk_bf16_f32 v106, v196, v197
	v_cvt_pk_bf16_f32 v107, v198, v199
	s_waitcnt lgkmcnt(0)
	v_cvt_pk_bf16_f32 v108, v200, v201
	v_cvt_pk_bf16_f32 v109, v202, v203
	v_addc_co_u32_e32 v129, vcc, 0, v123, vcc
	s_mov_b32 s10, 0x17000
	v_add_co_u32_e32 v168, vcc, s10, v122
	s_waitcnt vmcnt(9)
	v_mfma_f32_32x32x16_bf16 v[0:15], v[20:23], v[124:127], 0
	s_waitcnt vmcnt(8)
	v_addc_co_u32_e32 v169, vcc, 0, v123, vcc
	s_mov_b32 s11, 0x2d000
	v_add_co_u32_e32 v170, vcc, s11, v122
	v_mfma_f32_32x32x16_bf16 v[0:15], v[24:27], v[132:135], v[0:15]
	s_nop 0
	v_addc_co_u32_e32 v171, vcc, 0, v123, vcc
	s_waitcnt vmcnt(0)
	s_mov_b32 s12, 0x43000
	s_mov_b32 s13, 0xb1000
	s_mov_b32 s14, 0xc7000
	s_mov_b32 s15, 0xdd000
	v_mfma_f32_32x32x16_bf16 v[0:15], v[82:85], v[136:139], v[0:15]
	s_mov_b32 s16, 0xf3000
	s_mov_b32 s17, 0x161000
	s_mov_b32 s18, 0x177000
	s_mov_b32 s19, 0x18d000
	s_mov_b32 s20, 0x1a3000
	s_mov_b32 s21, 0x211000
	s_mov_b32 s22, 0x227000
	v_mfma_f32_32x32x16_bf16 v[0:15], v[86:89], v[140:143], v[0:15]
	s_mov_b32 s23, 0x23d000
	s_mov_b32 s30, 0x253000
	s_movk_i32 s8, 0x2000
	v_mfma_f32_32x32x16_bf16 v[0:15], v[90:93], v[144:147], v[0:15]
	v_mfma_f32_32x32x16_bf16 v[0:15], v[94:97], v[148:151], v[0:15]
	v_mfma_f32_32x32x16_bf16 v[0:15], v[98:101], v[152:155], v[0:15]
	v_mfma_f32_32x32x16_bf16 v[0:15], v[102:105], v[156:159], v[0:15]
	v_mfma_f32_32x32x16_bf16 v[0:15], v[110:113], v[160:163], v[0:15]
	v_mfma_f32_32x32x16_bf16 v[0:15], v[106:109], v[164:167], v[0:15]
	s_nop 11
	v_mul_f32_e32 v124, 0x3d372713, v0
	v_mul_f32_e32 v131, 0x3d372713, v2
	v_mul_f32_e32 v126, 0x3d372713, v1
	v_mul_f32_e32 v124, v0, v124
	v_mul_f32_e32 v131, v2, v131
	v_mul_f32_e32 v125, 0.5, v0
	v_mul_f32_e32 v132, 0.5, v2
	v_mul_f32_e32 v126, v1, v126
	v_fma_f32 v0, v0, v124, v0
	v_fma_f32 v2, v2, v131, v2
	v_mul_f32_e32 v127, 0.5, v1
	v_fma_f32 v1, v1, v126, v1
	v_mul_f32_e32 v0, 0x3f4c422a, v0
	v_mul_f32_e32 v2, 0x3f4c422a, v2
	v_mul_f32_e32 v133, 0x3d372713, v3
	v_mul_f32_e32 v1, 0x3f4c422a, v1
	v_add_f32_e32 v0, v0, v0
	v_add_f32_e32 v2, v2, v2
	v_mul_f32_e32 v133, v3, v133
; __device__ __forceinline__ unsigned f2bf(float f) { return cvtpk(f, 0.f); }
; __device__ __forceinline__ float gelu_tanh(float x) { const float u = 0.7978845608028654f * (x + 0.044715f * x * x * x); const float th = 1.0f - 2.0f * __builtin_amdgcn_rcpf(__expf(2.0f * u) + 1.0f); return 0.5f * x * (1.0f + th); }
; __device__ __forceinline__ int crow16(int g, int hh) { return (g & 3) + 8 * (g >> 2) + 4 * hh; }
; __device__ __forceinline__ void ssm_v2(const KA& A, const Ctx& F, int l, int b, int g) {
;     ...
;         bf16* op = PS + (tok0 + 2 * nt + (r32 >> 4)) * PSW + C_SSM + 16 * g + (r32 & 15);
; #pragma unroll
;         for (int q = 0; q < 16; ++q) { const bf16 gv_ = (bf16)f2bf(gelu_tanh(acc[q])); if (!(F.dry && (DRY_SEL & 2))) op[(size_t)(16 * crow16(q, hh)) * PSW] = gv_; }
	v_add_f32_e32 v1, v1, v1
	v_mul_f32_e32 v0, 0x3fb8aa3b, v0
	v_mul_f32_e32 v2, 0x3fb8aa3b, v2
	v_mul_f32_e32 v134, 0.5, v3
	v_fma_f32 v3, v3, v133, v3
	v_mul_f32_e32 v1, 0x3fb8aa3b, v1
	v_exp_f32_e32 v0, v0
	v_exp_f32_e32 v2, v2
	v_mul_f32_e32 v3, 0x3f4c422a, v3
	v_exp_f32_e32 v1, v1
	v_mul_f32_e32 v135, 0x3d372713, v4
	v_add_f32_e32 v3, v3, v3
	v_mul_f32_e32 v135, v4, v135
	v_mul_f32_e32 v3, 0x3fb8aa3b, v3
	v_fma_f32 v124, v4, v135, v4
	v_exp_f32_e32 v3, v3
	v_add_f32_e32 v0, 1.0, v0
	v_add_f32_e32 v2, 1.0, v2
	v_mul_f32_e32 v124, 0x3f4c422a, v124
	v_add_f32_e32 v1, 1.0, v1
	v_rcp_f32_e32 v0, v0
	v_rcp_f32_e32 v2, v2
	v_add_f32_e32 v124, v124, v124
	v_rcp_f32_e32 v1, v1
	v_mul_f32_e32 v124, 0x3fb8aa3b, v124
	v_exp_f32_e32 v124, v124
	v_add_f32_e32 v3, 1.0, v3
	v_rcp_f32_e32 v3, v3
	v_fma_f32 v0, v0, -2.0, 1.0
	v_fma_f32 v2, v2, -2.0, 1.0
	v_fma_f32 v1, v1, -2.0, 1.0
	v_add_f32_e32 v0, 1.0, v0
	v_add_f32_e32 v2, 1.0, v2
	v_add_f32_e32 v1, 1.0, v1
	v_mul_f32_e32 v0, v125, v0
	v_mul_f32_e32 v2, v132, v2
	v_add_f32_e32 v124, 1.0, v124
	v_mul_f32_e32 v1, v127, v1
	v_cvt_pk_bf16_f32 v0, v0, s0
	v_cvt_pk_bf16_f32 v2, v2, s0
	v_fma_f32 v3, v3, -2.0, 1.0
	v_cvt_pk_bf16_f32 v1, v1, s0
	global_store_short v[128:129], v0, off offset:1024
	global_store_short v[168:169], v1, off offset:1024
	global_store_short v[170:171], v2, off offset:1024
	v_rcp_f32_e32 v2, v124
	v_add_f32_e32 v3, 1.0, v3
	v_mul_f32_e32 v3, v134, v3
	v_add_co_u32_e32 v0, vcc, s12, v122
	v_cvt_pk_bf16_f32 v3, v3, s0
	s_nop 0
	v_addc_co_u32_e32 v1, vcc, 0, v123, vcc
	global_store_short v[0:1], v3, off offset:1024
	v_fma_f32 v0, v2, -2.0, 1.0
	v_mul_f32_e32 v2, 0x3d372713, v5
	v_mul_f32_e32 v2, v5, v2
	v_fma_f32 v2, v5, v2, v5
	v_mul_f32_e32 v2, 0x3f4c422a, v2
	v_add_f32_e32 v2, v2, v2
	v_mul_f32_e32 v2, 0x3fb8aa3b, v2
	v_exp_f32_e32 v2, v2
	v_mul_f32_e32 v1, 0.5, v4
	v_add_f32_e32 v0, 1.0, v0
	v_mul_f32_e32 v0, v1, v0
	v_cvt_pk_bf16_f32 v3, v0, s0
	v_add_f32_e32 v0, 1.0, v2
	v_rcp_f32_e32 v2, v0
	v_add_co_u32_e32 v0, vcc, s13, v122
	v_or_b32_e32 v124, 0x4000, v80
	s_nop 0
	v_addc_co_u32_e32 v1, vcc, 0, v123, vcc
	global_store_short v[0:1], v3, off offset:1024
	v_fma_f32 v0, v2, -2.0, 1.0
	v_mul_f32_e32 v2, 0x3d372713, v6
	v_mul_f32_e32 v2, v6, v2
	v_fma_f32 v2, v6, v2, v6
	v_mul_f32_e32 v2, 0x3f4c422a, v2
	v_add_f32_e32 v2, v2, v2
	v_mul_f32_e32 v2, 0x3fb8aa3b, v2
	v_exp_f32_e32 v2, v2
	v_mul_f32_e32 v1, 0.5, v5
	v_add_f32_e32 v0, 1.0, v0
	v_mul_f32_e32 v0, v1, v0
	v_cvt_pk_bf16_f32 v3, v0, s0
	v_add_f32_e32 v0, 1.0, v2
	v_rcp_f32_e32 v2, v0
	v_add_co_u32_e32 v0, vcc, s14, v122
	s_nop 1
	v_addc_co_u32_e32 v1, vcc, 0, v123, vcc
	global_store_short v[0:1], v3, off offset:1024
	v_fma_f32 v0, v2, -2.0, 1.0
	v_mul_f32_e32 v2, 0x3d372713, v7
	v_mul_f32_e32 v2, v7, v2
	v_fma_f32 v2, v7, v2, v7
	v_mul_f32_e32 v2, 0x3f4c422a, v2
	v_add_f32_e32 v2, v2, v2
	v_mul_f32_e32 v2, 0x3fb8aa3b, v2
	v_exp_f32_e32 v2, v2
	v_mul_f32_e32 v1, 0.5, v6
	v_add_f32_e32 v0, 1.0, v0
	v_mul_f32_e32 v0, v1, v0
	v_cvt_pk_bf16_f32 v3, v0, s0
	v_add_f32_e32 v0, 1.0, v2
	v_rcp_f32_e32 v2, v0
	v_add_co_u32_e32 v0, vcc, s15, v122
	s_nop 1
	v_addc_co_u32_e32 v1, vcc, 0, v123, vcc
	global_store_short v[0:1], v3, off offset:1024
	v_fma_f32 v0, v2, -2.0, 1.0
	v_mul_f32_e32 v2, 0x3d372713, v8
	v_mul_f32_e32 v2, v8, v2
	v_fma_f32 v2, v8, v2, v8
	v_mul_f32_e32 v2, 0x3f4c422a, v2
	v_add_f32_e32 v2, v2, v2
	v_mul_f32_e32 v2, 0x3fb8aa3b, v2
	v_exp_f32_e32 v2, v2
	v_mul_f32_e32 v1, 0.5, v7
	v_add_f32_e32 v0, 1.0, v0
	v_mul_f32_e32 v0, v1, v0
	v_cvt_pk_bf16_f32 v3, v0, s0
	v_add_f32_e32 v0, 1.0, v2
	v_rcp_f32_e32 v2, v0
	v_add_co_u32_e32 v0, vcc, s16, v122
	s_nop 1
	v_addc_co_u32_e32 v1, vcc, 0, v123, vcc
	global_store_short v[0:1], v3, off offset:1024
	v_fma_f32 v0, v2, -2.0, 1.0
	v_mul_f32_e32 v2, 0x3d372713, v9
	v_mul_f32_e32 v2, v9, v2
	v_fma_f32 v2, v9, v2, v9
	v_mul_f32_e32 v2, 0x3f4c422a, v2
	v_add_f32_e32 v2, v2, v2
	v_mul_f32_e32 v2, 0x3fb8aa3b, v2
	v_exp_f32_e32 v2, v2
	v_mul_f32_e32 v1, 0.5, v8
	v_add_f32_e32 v0, 1.0, v0
	v_mul_f32_e32 v0, v1, v0
	v_cvt_pk_bf16_f32 v3, v0, s0
	v_add_f32_e32 v0, 1.0, v2
	v_rcp_f32_e32 v2, v0
	v_add_co_u32_e32 v0, vcc, s17, v122
	s_nop 1
	v_addc_co_u32_e32 v1, vcc, 0, v123, vcc
	global_store_short v[0:1], v3, off offset:1024
	v_fma_f32 v0, v2, -2.0, 1.0
	v_mul_f32_e32 v2, 0x3d372713, v10
	v_mul_f32_e32 v2, v10, v2
	v_fma_f32 v2, v10, v2, v10
	v_mul_f32_e32 v2, 0x3f4c422a, v2
	v_add_f32_e32 v2, v2, v2
	v_mul_f32_e32 v2, 0x3fb8aa3b, v2
	v_exp_f32_e32 v2, v2
	v_mul_f32_e32 v1, 0.5, v9
	v_add_f32_e32 v0, 1.0, v0
	v_mul_f32_e32 v0, v1, v0
	v_cvt_pk_bf16_f32 v3, v0, s0
	v_add_f32_e32 v0, 1.0, v2
	v_rcp_f32_e32 v2, v0
	v_add_co_u32_e32 v0, vcc, s18, v122
	s_nop 1
	v_addc_co_u32_e32 v1, vcc, 0, v123, vcc
	global_store_short v[0:1], v3, off offset:1024
	v_fma_f32 v0, v2, -2.0, 1.0
	v_mul_f32_e32 v2, 0x3d372713, v11
	v_mul_f32_e32 v2, v11, v2
	v_fma_f32 v2, v11, v2, v11
	v_mul_f32_e32 v2, 0x3f4c422a, v2
	v_add_f32_e32 v2, v2, v2
	v_mul_f32_e32 v2, 0x3fb8aa3b, v2
	v_exp_f32_e32 v2, v2
	v_mul_f32_e32 v1, 0.5, v10
	v_add_f32_e32 v0, 1.0, v0
	v_mul_f32_e32 v0, v1, v0
	v_cvt_pk_bf16_f32 v3, v0, s0
	v_add_f32_e32 v0, 1.0, v2
	v_rcp_f32_e32 v2, v0
	v_add_co_u32_e32 v0, vcc, s19, v122
	s_nop 1
	v_addc_co_u32_e32 v1, vcc, 0, v123, vcc
	global_store_short v[0:1], v3, off offset:1024
	v_fma_f32 v0, v2, -2.0, 1.0
	v_mul_f32_e32 v2, 0x3d372713, v12
	v_mul_f32_e32 v2, v12, v2
	v_fma_f32 v2, v12, v2, v12
	v_mul_f32_e32 v2, 0x3f4c422a, v2
	v_add_f32_e32 v2, v2, v2
	v_mul_f32_e32 v2, 0x3fb8aa3b, v2
	v_exp_f32_e32 v2, v2
	v_mul_f32_e32 v1, 0.5, v11
	v_add_f32_e32 v0, 1.0, v0
	v_mul_f32_e32 v0, v1, v0
; __device__ __forceinline__ unsigned f2bf(float f) { return cvtpk(f, 0.f); }
; __device__ __forceinline__ float gelu_tanh(float x) { const float u = 0.7978845608028654f * (x + 0.044715f * x * x * x); const float th = 1.0f - 2.0f * __builtin_amdgcn_rcpf(__expf(2.0f * u) + 1.0f); return 0.5f * x * (1.0f + th); }
; __device__ __forceinline__ int crow16(int g, int hh) { return (g & 3) + 8 * (g >> 2) + 4 * hh; }
; __device__ __forceinline__ void ssm_v2(const KA& A, const Ctx& F, int l, int b, int g) {
;     ...
; #pragma unroll
;     for (int nt = 0; nt < 8; ++nt) if (sp_ & 4) {
;         f32x16 acc = {};
;         const bf16* tp = TM + (size_t)(nt * 16 * 64 + lane) * 8; const bf16* hp = HM + (size_t)(nt * 8 * 64 + lane) * 8;
;         { bf16x8_t tf[16], hf[8];
; #pragma unroll
;           for (int s = 0; s < 16; ++s) if (s <= 2 * nt + 1) tf[s] = *(const bf16x8_t*)(tp + s * 512);
; #pragma unroll
;           for (int s = 0; s < 8; ++s) hf[s] = *(const bf16x8_t*)(hp + s * 512);
; #pragma unroll
;           for (int s = 0; s < 16; ++s) if (s <= 2 * nt + 1) asm volatile("" :: "v"(tf[s]));
;           asm volatile("" :: "v"(hf[0]), "v"(hf[1]), "v"(hf[2]), "v"(hf[3]), "v"(hf[4]), "v"(hf[5]), "v"(hf[6]), "v"(hf[7]));
; #pragma unroll
;           for (int s = 0; s < 16; ++s) if (s <= 2 * nt + 1) acc = __builtin_amdgcn_mfma_f32_32x32x16_bf16(uf[s], tf[s], acc, 0, 0, 0);
; #pragma unroll
;           for (int s = 0; s < 8; ++s) acc = __builtin_amdgcn_mfma_f32_32x32x16_bf16(xf[s], hf[s], acc, 0, 0, 0); }
;         bf16* op = PS + (tok0 + 2 * nt + (r32 >> 4)) * PSW + C_SSM + 16 * g + (r32 & 15);
; #pragma unroll
;         for (int q = 0; q < 16; ++q) { const bf16 gv_ = (bf16)f2bf(gelu_tanh(acc[q])); if (!(F.dry && (DRY_SEL & 2))) op[(size_t)(16 * crow16(q, hh)) * PSW] = gv_; }
	v_cvt_pk_bf16_f32 v3, v0, s0
	v_add_f32_e32 v0, 1.0, v2
	v_rcp_f32_e32 v2, v0
	v_add_co_u32_e32 v0, vcc, s20, v122
	s_nop 1
	v_addc_co_u32_e32 v1, vcc, 0, v123, vcc
	global_store_short v[0:1], v3, off offset:1024
	v_fma_f32 v0, v2, -2.0, 1.0
	v_mul_f32_e32 v2, 0x3d372713, v13
	v_mul_f32_e32 v2, v13, v2
	v_fma_f32 v2, v13, v2, v13
	v_mul_f32_e32 v2, 0x3f4c422a, v2
	v_add_f32_e32 v2, v2, v2
	v_mul_f32_e32 v2, 0x3fb8aa3b, v2
	v_exp_f32_e32 v2, v2
	v_mul_f32_e32 v1, 0.5, v12
	v_add_f32_e32 v0, 1.0, v0
	v_mul_f32_e32 v0, v1, v0
	v_cvt_pk_bf16_f32 v3, v0, s0
	v_add_f32_e32 v0, 1.0, v2
	v_rcp_f32_e32 v2, v0
	v_add_co_u32_e32 v0, vcc, s21, v122
	s_nop 1
	v_addc_co_u32_e32 v1, vcc, 0, v123, vcc
	global_store_short v[0:1], v3, off offset:1024
	v_fma_f32 v0, v2, -2.0, 1.0
	v_mul_f32_e32 v2, 0x3d372713, v14
	v_mul_f32_e32 v2, v14, v2
	v_fma_f32 v2, v14, v2, v14
	v_mul_f32_e32 v2, 0x3f4c422a, v2
	v_add_f32_e32 v2, v2, v2
	v_mul_f32_e32 v2, 0x3fb8aa3b, v2
	v_exp_f32_e32 v2, v2
	v_mul_f32_e32 v1, 0.5, v13
	v_add_f32_e32 v0, 1.0, v0
	v_mul_f32_e32 v0, v1, v0
	v_cvt_pk_bf16_f32 v3, v0, s0
	v_add_f32_e32 v0, 1.0, v2
	v_rcp_f32_e32 v2, v0
	v_add_co_u32_e32 v0, vcc, s22, v122
	s_nop 1
	v_addc_co_u32_e32 v1, vcc, 0, v123, vcc
	global_store_short v[0:1], v3, off offset:1024
	v_fma_f32 v0, v2, -2.0, 1.0
	v_mul_f32_e32 v2, 0x3d372713, v15
	v_mul_f32_e32 v2, v15, v2
	v_fma_f32 v2, v15, v2, v15
	v_mul_f32_e32 v2, 0x3f4c422a, v2
	v_add_f32_e32 v2, v2, v2
	v_mul_f32_e32 v2, 0x3fb8aa3b, v2
	v_exp_f32_e32 v2, v2
	v_mul_f32_e32 v1, 0.5, v14
	v_add_f32_e32 v0, 1.0, v0
	v_mul_f32_e32 v0, v1, v0
	v_cvt_pk_bf16_f32 v3, v0, s0
	v_add_f32_e32 v0, 1.0, v2
	v_rcp_f32_e32 v2, v0
	v_add_co_u32_e32 v0, vcc, s23, v122
	s_nop 1
	v_addc_co_u32_e32 v1, vcc, 0, v123, vcc
	global_store_short v[0:1], v3, off offset:1024
	v_fma_f32 v0, v2, -2.0, 1.0
	v_mul_f32_e32 v1, 0.5, v15
	v_add_f32_e32 v0, 1.0, v0
	v_mul_f32_e32 v0, v1, v0
	v_cvt_pk_bf16_f32 v2, v0, s0
	v_add_co_u32_e32 v0, vcc, s30, v122
	s_nop 1
	v_addc_co_u32_e32 v1, vcc, 0, v123, vcc
	global_store_short v[0:1], v2, off offset:1024
	global_load_dwordx4 v[126:129], v124, s[4:5]
	global_load_dwordx4 v[132:135], v124, s[4:5] offset:1024
	global_load_dwordx4 v[140:143], v124, s[4:5] offset:2048
	global_load_dwordx4 v[144:147], v124, s[4:5] offset:3072
	v_lshl_add_u64 v[122:123], s[2:3], 0, v[80:81]
	v_add_co_u32_e32 v156, vcc, s8, v122
	s_movk_i32 s8, 0x3000
	s_nop 0
	v_addc_co_u32_e32 v157, vcc, 0, v123, vcc
	v_add_co_u32_e32 v172, vcc, s8, v122
	global_load_dwordx4 v[136:139], v[156:157], off offset:3072
	global_load_dwordx4 v[152:155], v[156:157], off offset:1024
	v_addc_co_u32_e32 v173, vcc, 0, v123, vcc
	global_load_dwordx4 v[148:151], v[172:173], off offset:-4096
	global_load_dwordx4 v[160:163], v[172:173], off
	global_load_dwordx4 v[164:167], v[172:173], off offset:1024
	s_waitcnt vmcnt(8)
	v_mfma_f32_32x32x16_bf16 v[0:15], v[20:23], v[126:129], 0
	global_load_dwordx4 v[156:159], v[156:157], off offset:2048
	s_nop 0
	global_load_dwordx4 v[168:171], v[172:173], off offset:2048
	s_nop 0
	global_load_dwordx4 v[172:175], v[172:173], off offset:3072
	v_or_b32_e32 v126, 2, v115
	s_waitcnt vmcnt(10)
	v_mfma_f32_32x32x16_bf16 v[0:15], v[24:27], v[132:135], v[0:15]
	v_mad_u64_u32 v[126:127], s[8:9], v126, s92, v[116:117]
	v_mad_i32_i24 v127, s7, v236, v127
	v_lshl_add_u64 v[126:127], v[126:127], 0, s[0:1]
	v_lshl_add_u64 v[126:127], v[126:127], 0, v[120:121]
	v_lshl_add_u64 v[126:127], v[126:127], 0, v[118:119]
	s_waitcnt vmcnt(9)
	v_mfma_f32_32x32x16_bf16 v[0:15], v[28:31], v[140:143], v[0:15]
	s_waitcnt vmcnt(8)
	s_waitcnt vmcnt(0)
	v_mfma_f32_32x32x16_bf16 v[0:15], v[16:19], v[144:147], v[0:15]
	v_mfma_f32_32x32x16_bf16 v[0:15], v[82:85], v[148:151], v[0:15]
	v_mfma_f32_32x32x16_bf16 v[0:15], v[86:89], v[152:155], v[0:15]
	v_mfma_f32_32x32x16_bf16 v[0:15], v[90:93], v[156:159], v[0:15]
	v_mfma_f32_32x32x16_bf16 v[0:15], v[94:97], v[136:139], v[0:15]
	v_mfma_f32_32x32x16_bf16 v[0:15], v[98:101], v[160:163], v[0:15]
	v_mfma_f32_32x32x16_bf16 v[0:15], v[102:105], v[164:167], v[0:15]
	v_mfma_f32_32x32x16_bf16 v[0:15], v[110:113], v[168:171], v[0:15]
	v_mfma_f32_32x32x16_bf16 v[0:15], v[106:109], v[172:175], v[0:15]
	s_nop 11
	v_mul_f32_e32 v125, 0x3d372713, v0
	v_mul_f32_e32 v125, v0, v125
	v_fma_f32 v125, v0, v125, v0
	v_mul_f32_e32 v125, 0x3f4c422a, v125
	v_add_f32_e32 v125, v125, v125
	v_mul_f32_e32 v125, 0x3fb8aa3b, v125
	v_exp_f32_e32 v125, v125
	v_mul_f32_e32 v128, 0x3d372713, v1
	v_mul_f32_e32 v128, v1, v128
	v_fma_f32 v128, v1, v128, v1
	v_add_f32_e32 v125, 1.0, v125
	v_mul_f32_e32 v128, 0x3f4c422a, v128
	v_rcp_f32_e32 v125, v125
	v_add_f32_e32 v128, v128, v128
	v_mul_f32_e32 v128, 0x3fb8aa3b, v128
	v_exp_f32_e32 v128, v128
	v_fma_f32 v125, v125, -2.0, 1.0
	v_mul_f32_e32 v0, 0.5, v0
	v_add_f32_e32 v125, 1.0, v125
	v_mul_f32_e32 v0, v0, v125
	v_add_f32_e32 v125, 1.0, v128
	v_rcp_f32_e32 v125, v125
	v_add_co_u32_e32 v128, vcc, s66, v126
	v_cvt_pk_bf16_f32 v0, v0, s0
	s_nop 0
	v_addc_co_u32_e32 v129, vcc, 0, v127, vcc
	global_store_short v[128:129], v0, off offset:1024
	v_fma_f32 v0, v125, -2.0, 1.0
	v_mul_f32_e32 v125, 0x3d372713, v2
	v_mul_f32_e32 v125, v2, v125
	v_fma_f32 v125, v2, v125, v2
	v_mul_f32_e32 v125, 0x3f4c422a, v125
	v_add_f32_e32 v125, v125, v125
	v_mul_f32_e32 v125, 0x3fb8aa3b, v125
	v_exp_f32_e32 v125, v125
	v_mul_f32_e32 v1, 0.5, v1
	v_add_f32_e32 v0, 1.0, v0
	v_mul_f32_e32 v0, v1, v0
	v_cvt_pk_bf16_f32 v128, v0, s0
	v_add_f32_e32 v0, 1.0, v125
	v_rcp_f32_e32 v125, v0
	v_add_co_u32_e32 v0, vcc, s10, v126
	v_mov_b32_e32 v129, v81
	s_nop 0
	v_addc_co_u32_e32 v1, vcc, 0, v127, vcc
	global_store_short v[0:1], v128, off offset:1024
; __device__ __forceinline__ unsigned f2bf(float f) { return cvtpk(f, 0.f); }
; __device__ __forceinline__ float gelu_tanh(float x) { const float u = 0.7978845608028654f * (x + 0.044715f * x * x * x); const float th = 1.0f - 2.0f * __builtin_amdgcn_rcpf(__expf(2.0f * u) + 1.0f); return 0.5f * x * (1.0f + th); }
; __device__ __forceinline__ int crow16(int g, int hh) { return (g & 3) + 8 * (g >> 2) + 4 * hh; }
; __device__ __forceinline__ void ssm_v2(const KA& A, const Ctx& F, int l, int b, int g) {
;     ...
;         bf16* op = PS + (tok0 + 2 * nt + (r32 >> 4)) * PSW + C_SSM + 16 * g + (r32 & 15);
; #pragma unroll
;         for (int q = 0; q < 16; ++q) { const bf16 gv_ = (bf16)f2bf(gelu_tanh(acc[q])); if (!(F.dry && (DRY_SEL & 2))) op[(size_t)(16 * crow16(q, hh)) * PSW] = gv_; }
	v_mul_f32_e32 v1, 0.5, v2
	v_mul_f32_e32 v2, 0x3d372713, v3
	v_mul_f32_e32 v2, v3, v2
	v_fma_f32 v2, v3, v2, v3
	v_mul_f32_e32 v2, 0x3f4c422a, v2
	v_add_f32_e32 v2, v2, v2
	v_mul_f32_e32 v2, 0x3fb8aa3b, v2
	v_exp_f32_e32 v2, v2
	v_fma_f32 v0, v125, -2.0, 1.0
	v_add_f32_e32 v0, 1.0, v0
	v_mul_f32_e32 v0, v1, v0
	v_cvt_pk_bf16_f32 v125, v0, s0
	v_add_f32_e32 v0, 1.0, v2
	v_rcp_f32_e32 v2, v0
	v_add_co_u32_e32 v0, vcc, s11, v126
	v_or_b32_e32 v128, 0x8000, v80
	s_nop 0
	v_addc_co_u32_e32 v1, vcc, 0, v127, vcc
	global_store_short v[0:1], v125, off offset:1024
	v_fma_f32 v0, v2, -2.0, 1.0
	v_mul_f32_e32 v2, 0x3d372713, v4
	v_mul_f32_e32 v2, v4, v2
	v_fma_f32 v2, v4, v2, v4
	v_mul_f32_e32 v2, 0x3f4c422a, v2
	v_add_f32_e32 v2, v2, v2
	v_mul_f32_e32 v2, 0x3fb8aa3b, v2
	v_exp_f32_e32 v2, v2
	v_mul_f32_e32 v1, 0.5, v3
	v_add_f32_e32 v0, 1.0, v0
	v_mul_f32_e32 v0, v1, v0
	v_cvt_pk_bf16_f32 v3, v0, s0
	v_add_f32_e32 v0, 1.0, v2
	v_rcp_f32_e32 v2, v0
	v_add_co_u32_e32 v0, vcc, s12, v126
	v_mov_b32_e32 v125, v81
	s_nop 0
	v_addc_co_u32_e32 v1, vcc, 0, v127, vcc
	global_store_short v[0:1], v3, off offset:1024
	v_fma_f32 v0, v2, -2.0, 1.0
	v_mul_f32_e32 v2, 0x3d372713, v5
	v_mul_f32_e32 v2, v5, v2
	v_fma_f32 v2, v5, v2, v5
	v_mul_f32_e32 v2, 0x3f4c422a, v2
	v_add_f32_e32 v2, v2, v2
	v_mul_f32_e32 v2, 0x3fb8aa3b, v2
	v_exp_f32_e32 v2, v2
	v_mul_f32_e32 v1, 0.5, v4
	v_add_f32_e32 v0, 1.0, v0
	v_mul_f32_e32 v0, v1, v0
	v_cvt_pk_bf16_f32 v3, v0, s0
	v_add_f32_e32 v0, 1.0, v2
	v_rcp_f32_e32 v2, v0
	v_add_co_u32_e32 v0, vcc, s13, v126
	s_nop 1
	v_addc_co_u32_e32 v1, vcc, 0, v127, vcc
	global_store_short v[0:1], v3, off offset:1024
	v_fma_f32 v0, v2, -2.0, 1.0
	v_mul_f32_e32 v2, 0x3d372713, v6
	v_mul_f32_e32 v2, v6, v2
	v_fma_f32 v2, v6, v2, v6
	v_mul_f32_e32 v2, 0x3f4c422a, v2
	v_add_f32_e32 v2, v2, v2
	v_mul_f32_e32 v2, 0x3fb8aa3b, v2
	v_exp_f32_e32 v2, v2
	v_mul_f32_e32 v1, 0.5, v5
	v_add_f32_e32 v0, 1.0, v0
	v_mul_f32_e32 v0, v1, v0
	v_cvt_pk_bf16_f32 v3, v0, s0
	v_add_f32_e32 v0, 1.0, v2
	v_rcp_f32_e32 v2, v0
	v_add_co_u32_e32 v0, vcc, s14, v126
	s_nop 1
	v_addc_co_u32_e32 v1, vcc, 0, v127, vcc
	global_store_short v[0:1], v3, off offset:1024
	v_fma_f32 v0, v2, -2.0, 1.0
	v_mul_f32_e32 v2, 0x3d372713, v7
	v_mul_f32_e32 v2, v7, v2
	v_fma_f32 v2, v7, v2, v7
	v_mul_f32_e32 v2, 0x3f4c422a, v2
	v_add_f32_e32 v2, v2, v2
	v_mul_f32_e32 v2, 0x3fb8aa3b, v2
	v_exp_f32_e32 v2, v2
	v_mul_f32_e32 v1, 0.5, v6
	v_add_f32_e32 v0, 1.0, v0
	v_mul_f32_e32 v0, v1, v0
	v_cvt_pk_bf16_f32 v3, v0, s0
	v_add_f32_e32 v0, 1.0, v2
	v_rcp_f32_e32 v2, v0
	v_add_co_u32_e32 v0, vcc, s15, v126
	s_nop 1
	v_addc_co_u32_e32 v1, vcc, 0, v127, vcc
	global_store_short v[0:1], v3, off offset:1024
	v_fma_f32 v0, v2, -2.0, 1.0
	v_mul_f32_e32 v2, 0x3d372713, v8
	v_mul_f32_e32 v2, v8, v2
	v_fma_f32 v2, v8, v2, v8
	v_mul_f32_e32 v2, 0x3f4c422a, v2
	v_add_f32_e32 v2, v2, v2
	v_mul_f32_e32 v2, 0x3fb8aa3b, v2
	v_exp_f32_e32 v2, v2
	v_mul_f32_e32 v1, 0.5, v7
	v_add_f32_e32 v0, 1.0, v0
	v_mul_f32_e32 v0, v1, v0
	v_cvt_pk_bf16_f32 v3, v0, s0
	v_add_f32_e32 v0, 1.0, v2
	v_rcp_f32_e32 v2, v0
	v_add_co_u32_e32 v0, vcc, s16, v126
	s_nop 1
	v_addc_co_u32_e32 v1, vcc, 0, v127, vcc
	global_store_short v[0:1], v3, off offset:1024
	v_fma_f32 v0, v2, -2.0, 1.0
	v_mul_f32_e32 v2, 0x3d372713, v9
	v_mul_f32_e32 v2, v9, v2
	v_fma_f32 v2, v9, v2, v9
	v_mul_f32_e32 v2, 0x3f4c422a, v2
	v_add_f32_e32 v2, v2, v2
	v_mul_f32_e32 v2, 0x3fb8aa3b, v2
	v_exp_f32_e32 v2, v2
	v_mul_f32_e32 v1, 0.5, v8
	v_add_f32_e32 v0, 1.0, v0
	v_mul_f32_e32 v0, v1, v0
	v_cvt_pk_bf16_f32 v3, v0, s0
	v_add_f32_e32 v0, 1.0, v2
	v_rcp_f32_e32 v2, v0
	v_add_co_u32_e32 v0, vcc, s17, v126
	s_nop 1
	v_addc_co_u32_e32 v1, vcc, 0, v127, vcc
	global_store_short v[0:1], v3, off offset:1024
	v_fma_f32 v0, v2, -2.0, 1.0
	v_mul_f32_e32 v2, 0x3d372713, v10
	v_mul_f32_e32 v2, v10, v2
	v_fma_f32 v2, v10, v2, v10
	v_mul_f32_e32 v2, 0x3f4c422a, v2
	v_add_f32_e32 v2, v2, v2
	v_mul_f32_e32 v2, 0x3fb8aa3b, v2
	v_exp_f32_e32 v2, v2
	v_mul_f32_e32 v1, 0.5, v9
	v_add_f32_e32 v0, 1.0, v0
	v_mul_f32_e32 v0, v1, v0
	v_cvt_pk_bf16_f32 v3, v0, s0
	v_add_f32_e32 v0, 1.0, v2
	v_rcp_f32_e32 v2, v0
	v_add_co_u32_e32 v0, vcc, s18, v126
	s_nop 1
	v_addc_co_u32_e32 v1, vcc, 0, v127, vcc
	global_store_short v[0:1], v3, off offset:1024
	v_fma_f32 v0, v2, -2.0, 1.0
	v_mul_f32_e32 v2, 0x3d372713, v11
	v_mul_f32_e32 v2, v11, v2
	v_fma_f32 v2, v11, v2, v11
	v_mul_f32_e32 v2, 0x3f4c422a, v2
	v_add_f32_e32 v2, v2, v2
	v_mul_f32_e32 v2, 0x3fb8aa3b, v2
	v_exp_f32_e32 v2, v2
	v_mul_f32_e32 v1, 0.5, v10
	v_add_f32_e32 v0, 1.0, v0
	v_mul_f32_e32 v0, v1, v0
	v_cvt_pk_bf16_f32 v3, v0, s0
	v_add_f32_e32 v0, 1.0, v2
	v_rcp_f32_e32 v2, v0
	v_add_co_u32_e32 v0, vcc, s19, v126
	s_nop 1
	v_addc_co_u32_e32 v1, vcc, 0, v127, vcc
	global_store_short v[0:1], v3, off offset:1024
	v_fma_f32 v0, v2, -2.0, 1.0
	v_mul_f32_e32 v2, 0x3d372713, v12
	v_mul_f32_e32 v2, v12, v2
	v_fma_f32 v2, v12, v2, v12
	v_mul_f32_e32 v2, 0x3f4c422a, v2
	v_add_f32_e32 v2, v2, v2
	v_mul_f32_e32 v2, 0x3fb8aa3b, v2
	v_exp_f32_e32 v2, v2
	v_mul_f32_e32 v1, 0.5, v11
	v_add_f32_e32 v0, 1.0, v0
	v_mul_f32_e32 v0, v1, v0
	v_cvt_pk_bf16_f32 v3, v0, s0
	v_add_f32_e32 v0, 1.0, v2
	v_rcp_f32_e32 v2, v0
	v_add_co_u32_e32 v0, vcc, s20, v126
	s_nop 1
	v_addc_co_u32_e32 v1, vcc, 0, v127, vcc
	global_store_short v[0:1], v3, off offset:1024
	v_fma_f32 v0, v2, -2.0, 1.0
	v_mul_f32_e32 v2, 0x3d372713, v13
	v_mul_f32_e32 v2, v13, v2
	v_fma_f32 v2, v13, v2, v13
	v_mul_f32_e32 v2, 0x3f4c422a, v2
	v_add_f32_e32 v2, v2, v2
	v_mul_f32_e32 v2, 0x3fb8aa3b, v2
	v_exp_f32_e32 v2, v2
	v_mul_f32_e32 v1, 0.5, v12
	v_add_f32_e32 v0, 1.0, v0
	v_mul_f32_e32 v0, v1, v0
; __device__ __forceinline__ unsigned f2bf(float f) { return cvtpk(f, 0.f); }
; __device__ __forceinline__ float gelu_tanh(float x) { const float u = 0.7978845608028654f * (x + 0.044715f * x * x * x); const float th = 1.0f - 2.0f * __builtin_amdgcn_rcpf(__expf(2.0f * u) + 1.0f); return 0.5f * x * (1.0f + th); }
; __device__ __forceinline__ int crow16(int g, int hh) { return (g & 3) + 8 * (g >> 2) + 4 * hh; }
; __device__ __forceinline__ void ssm_v2(const KA& A, const Ctx& F, int l, int b, int g) {
;     ...
; #pragma unroll
;     for (int nt = 0; nt < 8; ++nt) if (sp_ & 4) {
;         f32x16 acc = {};
;         const bf16* tp = TM + (size_t)(nt * 16 * 64 + lane) * 8; const bf16* hp = HM + (size_t)(nt * 8 * 64 + lane) * 8;
;         { bf16x8_t tf[16], hf[8];
; #pragma unroll
;           for (int s = 0; s < 16; ++s) if (s <= 2 * nt + 1) tf[s] = *(const bf16x8_t*)(tp + s * 512);
; #pragma unroll
;           for (int s = 0; s < 8; ++s) hf[s] = *(const bf16x8_t*)(hp + s * 512);
; #pragma unroll
;           for (int s = 0; s < 16; ++s) if (s <= 2 * nt + 1) asm volatile("" :: "v"(tf[s]));
;           asm volatile("" :: "v"(hf[0]), "v"(hf[1]), "v"(hf[2]), "v"(hf[3]), "v"(hf[4]), "v"(hf[5]), "v"(hf[6]), "v"(hf[7]));
; #pragma unroll
;           for (int s = 0; s < 16; ++s) if (s <= 2 * nt + 1) acc = __builtin_amdgcn_mfma_f32_32x32x16_bf16(uf[s], tf[s], acc, 0, 0, 0);
; #pragma unroll
;           for (int s = 0; s < 8; ++s) acc = __builtin_amdgcn_mfma_f32_32x32x16_bf16(xf[s], hf[s], acc, 0, 0, 0); }
;         bf16* op = PS + (tok0 + 2 * nt + (r32 >> 4)) * PSW + C_SSM + 16 * g + (r32 & 15);
; #pragma unroll
;         for (int q = 0; q < 16; ++q) { const bf16 gv_ = (bf16)f2bf(gelu_tanh(acc[q])); if (!(F.dry && (DRY_SEL & 2))) op[(size_t)(16 * crow16(q, hh)) * PSW] = gv_; }
	v_cvt_pk_bf16_f32 v3, v0, s0
	v_add_f32_e32 v0, 1.0, v2
	v_rcp_f32_e32 v2, v0
	v_add_co_u32_e32 v0, vcc, s21, v126
	s_nop 1
	v_addc_co_u32_e32 v1, vcc, 0, v127, vcc
	global_store_short v[0:1], v3, off offset:1024
	v_fma_f32 v0, v2, -2.0, 1.0
	v_mul_f32_e32 v2, 0x3d372713, v14
	v_mul_f32_e32 v2, v14, v2
	v_fma_f32 v2, v14, v2, v14
	v_mul_f32_e32 v2, 0x3f4c422a, v2
	v_add_f32_e32 v2, v2, v2
	v_mul_f32_e32 v2, 0x3fb8aa3b, v2
	v_exp_f32_e32 v2, v2
	v_mul_f32_e32 v1, 0.5, v13
	v_add_f32_e32 v0, 1.0, v0
	v_mul_f32_e32 v0, v1, v0
	v_cvt_pk_bf16_f32 v3, v0, s0
	v_add_f32_e32 v0, 1.0, v2
	v_rcp_f32_e32 v2, v0
	v_add_co_u32_e32 v0, vcc, s22, v126
	s_nop 1
	v_addc_co_u32_e32 v1, vcc, 0, v127, vcc
	global_store_short v[0:1], v3, off offset:1024
	v_fma_f32 v0, v2, -2.0, 1.0
	v_mul_f32_e32 v2, 0x3d372713, v15
	v_mul_f32_e32 v2, v15, v2
	v_fma_f32 v2, v15, v2, v15
	v_mul_f32_e32 v2, 0x3f4c422a, v2
	v_add_f32_e32 v2, v2, v2
	v_mul_f32_e32 v2, 0x3fb8aa3b, v2
	v_exp_f32_e32 v2, v2
	v_mul_f32_e32 v1, 0.5, v14
	v_add_f32_e32 v0, 1.0, v0
	v_mul_f32_e32 v0, v1, v0
	v_cvt_pk_bf16_f32 v3, v0, s0
	v_add_f32_e32 v0, 1.0, v2
	v_rcp_f32_e32 v2, v0
	v_add_co_u32_e32 v0, vcc, s23, v126
	s_nop 1
	v_addc_co_u32_e32 v1, vcc, 0, v127, vcc
	global_store_short v[0:1], v3, off offset:1024
	v_fma_f32 v0, v2, -2.0, 1.0
	v_mul_f32_e32 v1, 0.5, v15
	v_add_f32_e32 v0, 1.0, v0
	v_mul_f32_e32 v0, v1, v0
	v_cvt_pk_bf16_f32 v2, v0, s0
	v_add_co_u32_e32 v0, vcc, s30, v126
	s_nop 1
	v_addc_co_u32_e32 v1, vcc, 0, v127, vcc
	global_store_short v[0:1], v2, off offset:1024
	global_load_dwordx4 v[132:135], v128, s[4:5]
	global_load_dwordx4 v[136:139], v128, s[4:5] offset:1024
	global_load_dwordx4 v[140:143], v128, s[4:5] offset:2048
	global_load_dwordx4 v[144:147], v128, s[4:5] offset:3072
	v_lshl_add_u64 v[126:127], s[4:5], 0, v[128:129]
	v_add_co_u32_e32 v126, vcc, s66, v126
	global_load_dwordx4 v[156:159], v124, s[2:3]
	global_load_dwordx4 v[160:163], v124, s[2:3] offset:1024
	v_addc_co_u32_e32 v127, vcc, 0, v127, vcc
	global_load_dwordx4 v[148:151], v[126:127], off
	global_load_dwordx4 v[152:155], v[126:127], off offset:1024
	global_load_dwordx4 v[164:167], v124, s[2:3] offset:2048
	global_load_dwordx4 v[168:171], v124, s[2:3] offset:3072
	v_lshl_add_u64 v[124:125], s[2:3], 0, v[124:125]
	v_add_co_u32_e32 v180, vcc, s66, v124
	s_waitcnt vmcnt(9)
	v_mfma_f32_32x32x16_bf16 v[0:15], v[20:23], v[132:135], 0
	v_addc_co_u32_e32 v181, vcc, 0, v125, vcc
	global_load_dwordx4 v[124:127], v[180:181], off
	global_load_dwordx4 v[172:175], v[180:181], off offset:1024
	global_load_dwordx4 v[176:179], v[180:181], off offset:2048
	global_load_dwordx4 v[184:187], v[180:181], off offset:3072
	s_waitcnt vmcnt(12)
	v_mfma_f32_32x32x16_bf16 v[0:15], v[24:27], v[136:139], v[0:15]
	s_waitcnt vmcnt(11)
	s_waitcnt vmcnt(10)
	s_waitcnt vmcnt(7)
	s_waitcnt vmcnt(6)
	s_waitcnt vmcnt(0)
	v_mfma_f32_32x32x16_bf16 v[0:15], v[28:31], v[140:143], v[0:15]
	v_mfma_f32_32x32x16_bf16 v[0:15], v[16:19], v[144:147], v[0:15]
	v_mfma_f32_32x32x16_bf16 v[0:15], v[32:35], v[148:151], v[0:15]
	v_mfma_f32_32x32x16_bf16 v[0:15], v[36:39], v[152:155], v[0:15]
	v_mfma_f32_32x32x16_bf16 v[0:15], v[82:85], v[156:159], v[0:15]
	v_mfma_f32_32x32x16_bf16 v[0:15], v[86:89], v[160:163], v[0:15]
	v_mfma_f32_32x32x16_bf16 v[0:15], v[90:93], v[164:167], v[0:15]
	v_mfma_f32_32x32x16_bf16 v[0:15], v[94:97], v[168:171], v[0:15]
	v_mfma_f32_32x32x16_bf16 v[0:15], v[98:101], v[124:127], v[0:15]
	v_mfma_f32_32x32x16_bf16 v[0:15], v[102:105], v[172:175], v[0:15]
	v_mfma_f32_32x32x16_bf16 v[0:15], v[110:113], v[176:179], v[0:15]
	v_mfma_f32_32x32x16_bf16 v[0:15], v[106:109], v[184:187], v[0:15]
	s_nop 11
	v_mul_f32_e32 v124, 0x3d372713, v0
	v_mul_f32_e32 v124, v0, v124
	v_fma_f32 v124, v0, v124, v0
	v_mul_f32_e32 v124, 0x3f4c422a, v124
	v_add_f32_e32 v124, v124, v124
	v_mul_f32_e32 v124, 0x3fb8aa3b, v124
	v_exp_f32_e32 v126, v124
	v_mul_f32_e32 v127, 0x3d372713, v1
	v_mul_f32_e32 v127, v1, v127
	v_fma_f32 v127, v1, v127, v1
	v_add_f32_e32 v126, 1.0, v126
	v_mul_f32_e32 v127, 0x3f4c422a, v127
	v_rcp_f32_e32 v126, v126
	v_add_f32_e32 v127, v127, v127
	v_or_b32_e32 v124, 4, v115
	v_mul_f32_e32 v127, 0x3fb8aa3b, v127
	v_mad_u64_u32 v[124:125], s[8:9], v124, s92, v[116:117]
	v_exp_f32_e32 v127, v127
	v_mad_i32_i24 v125, s7, v236, v125
	v_lshl_add_u64 v[124:125], v[124:125], 0, s[0:1]
	v_fma_f32 v126, v126, -2.0, 1.0
	v_lshl_add_u64 v[124:125], v[124:125], 0, v[120:121]
	v_mul_f32_e32 v0, 0.5, v0
	v_add_f32_e32 v126, 1.0, v126
	v_mul_f32_e32 v0, v0, v126
	v_lshl_add_u64 v[124:125], v[124:125], 0, v[118:119]
	v_add_f32_e32 v126, 1.0, v127
	v_rcp_f32_e32 v131, v126
	v_add_co_u32_e32 v126, vcc, s66, v124
	v_cvt_pk_bf16_f32 v0, v0, s0
	s_nop 0
	v_addc_co_u32_e32 v127, vcc, 0, v125, vcc
	global_store_short v[126:127], v0, off offset:1024
	v_mul_f32_e32 v126, 0x3d372713, v2
	v_mul_f32_e32 v126, v2, v126
	v_fma_f32 v126, v2, v126, v2
	v_mul_f32_e32 v126, 0x3f4c422a, v126
	v_add_f32_e32 v126, v126, v126
	v_mul_f32_e32 v126, 0x3fb8aa3b, v126
	v_exp_f32_e32 v126, v126
	v_fma_f32 v0, v131, -2.0, 1.0
	v_mul_f32_e32 v1, 0.5, v1
	v_add_f32_e32 v0, 1.0, v0
	v_mul_f32_e32 v0, v1, v0
	v_cvt_pk_bf16_f32 v127, v0, s0
	v_add_f32_e32 v0, 1.0, v126
	v_rcp_f32_e32 v126, v0
	v_add_co_u32_e32 v0, vcc, s10, v124
	s_movk_i32 s8, 0x6000
	s_nop 0
	v_addc_co_u32_e32 v1, vcc, 0, v125, vcc
	global_store_short v[0:1], v127, off offset:1024
	v_mul_f32_e32 v1, 0.5, v2
	v_mul_f32_e32 v2, 0x3d372713, v3
	v_mul_f32_e32 v2, v3, v2
	v_fma_f32 v2, v3, v2, v3
	v_mul_f32_e32 v2, 0x3f4c422a, v2
	v_add_f32_e32 v2, v2, v2
	v_mul_f32_e32 v2, 0x3fb8aa3b, v2
	v_exp_f32_e32 v2, v2
	v_fma_f32 v0, v126, -2.0, 1.0
; __device__ __forceinline__ unsigned f2bf(float f) { return cvtpk(f, 0.f); }
; __device__ __forceinline__ float gelu_tanh(float x) { const float u = 0.7978845608028654f * (x + 0.044715f * x * x * x); const float th = 1.0f - 2.0f * __builtin_amdgcn_rcpf(__expf(2.0f * u) + 1.0f); return 0.5f * x * (1.0f + th); }
; __device__ __forceinline__ int crow16(int g, int hh) { return (g & 3) + 8 * (g >> 2) + 4 * hh; }
; __device__ __forceinline__ void ssm_v2(const KA& A, const Ctx& F, int l, int b, int g) {
;     ...
;         bf16* op = PS + (tok0 + 2 * nt + (r32 >> 4)) * PSW + C_SSM + 16 * g + (r32 & 15);
; #pragma unroll
;         for (int q = 0; q < 16; ++q) { const bf16 gv_ = (bf16)f2bf(gelu_tanh(acc[q])); if (!(F.dry && (DRY_SEL & 2))) op[(size_t)(16 * crow16(q, hh)) * PSW] = gv_; }
	v_add_f32_e32 v0, 1.0, v0
	v_mul_f32_e32 v0, v1, v0
	v_cvt_pk_bf16_f32 v126, v0, s0
	v_add_f32_e32 v0, 1.0, v2
	v_rcp_f32_e32 v2, v0
	v_add_co_u32_e32 v0, vcc, s11, v124
	s_nop 1
	v_addc_co_u32_e32 v1, vcc, 0, v125, vcc
	global_store_short v[0:1], v126, off offset:1024
	v_fma_f32 v0, v2, -2.0, 1.0
	v_mul_f32_e32 v2, 0x3d372713, v4
	v_mul_f32_e32 v2, v4, v2
	v_fma_f32 v2, v4, v2, v4
	v_mul_f32_e32 v2, 0x3f4c422a, v2
	v_add_f32_e32 v2, v2, v2
	v_mul_f32_e32 v2, 0x3fb8aa3b, v2
	v_exp_f32_e32 v2, v2
	v_mul_f32_e32 v1, 0.5, v3
	v_add_f32_e32 v0, 1.0, v0
	v_mul_f32_e32 v0, v1, v0
	v_cvt_pk_bf16_f32 v3, v0, s0
	v_add_f32_e32 v0, 1.0, v2
	v_rcp_f32_e32 v2, v0
	v_add_co_u32_e32 v0, vcc, s12, v124
	s_nop 1
	v_addc_co_u32_e32 v1, vcc, 0, v125, vcc
	global_store_short v[0:1], v3, off offset:1024
	v_fma_f32 v0, v2, -2.0, 1.0
	v_mul_f32_e32 v2, 0x3d372713, v5
	v_mul_f32_e32 v2, v5, v2
	v_fma_f32 v2, v5, v2, v5
	v_mul_f32_e32 v2, 0x3f4c422a, v2
	v_add_f32_e32 v2, v2, v2
	v_mul_f32_e32 v2, 0x3fb8aa3b, v2
	v_exp_f32_e32 v2, v2
	v_mul_f32_e32 v1, 0.5, v4
	v_add_f32_e32 v0, 1.0, v0
	v_mul_f32_e32 v0, v1, v0
	v_cvt_pk_bf16_f32 v3, v0, s0
	v_add_f32_e32 v0, 1.0, v2
	v_rcp_f32_e32 v2, v0
	v_add_co_u32_e32 v0, vcc, s13, v124
	s_nop 1
	v_addc_co_u32_e32 v1, vcc, 0, v125, vcc
	global_store_short v[0:1], v3, off offset:1024
	v_fma_f32 v0, v2, -2.0, 1.0
	v_mul_f32_e32 v2, 0x3d372713, v6
	v_mul_f32_e32 v2, v6, v2
	v_fma_f32 v2, v6, v2, v6
	v_mul_f32_e32 v2, 0x3f4c422a, v2
	v_add_f32_e32 v2, v2, v2
	v_mul_f32_e32 v2, 0x3fb8aa3b, v2
	v_exp_f32_e32 v2, v2
	v_mul_f32_e32 v1, 0.5, v5
	v_add_f32_e32 v0, 1.0, v0
	v_mul_f32_e32 v0, v1, v0
	v_cvt_pk_bf16_f32 v3, v0, s0
	v_add_f32_e32 v0, 1.0, v2
	v_rcp_f32_e32 v2, v0
	v_add_co_u32_e32 v0, vcc, s14, v124
	s_nop 1
	v_addc_co_u32_e32 v1, vcc, 0, v125, vcc
	global_store_short v[0:1], v3, off offset:1024
	v_fma_f32 v0, v2, -2.0, 1.0
	v_mul_f32_e32 v2, 0x3d372713, v7
	v_mul_f32_e32 v2, v7, v2
	v_fma_f32 v2, v7, v2, v7
	v_mul_f32_e32 v2, 0x3f4c422a, v2
	v_add_f32_e32 v2, v2, v2
	v_mul_f32_e32 v2, 0x3fb8aa3b, v2
	v_exp_f32_e32 v2, v2
	v_mul_f32_e32 v1, 0.5, v6
	v_add_f32_e32 v0, 1.0, v0
	v_mul_f32_e32 v0, v1, v0
	v_cvt_pk_bf16_f32 v3, v0, s0
	v_add_f32_e32 v0, 1.0, v2
	v_rcp_f32_e32 v2, v0
	v_add_co_u32_e32 v0, vcc, s15, v124
	s_nop 1
	v_addc_co_u32_e32 v1, vcc, 0, v125, vcc
	global_store_short v[0:1], v3, off offset:1024
	v_fma_f32 v0, v2, -2.0, 1.0
	v_mul_f32_e32 v2, 0x3d372713, v8
	v_mul_f32_e32 v2, v8, v2
	v_fma_f32 v2, v8, v2, v8
	v_mul_f32_e32 v2, 0x3f4c422a, v2
	v_add_f32_e32 v2, v2, v2
	v_mul_f32_e32 v2, 0x3fb8aa3b, v2
	v_exp_f32_e32 v2, v2
	v_mul_f32_e32 v1, 0.5, v7
	v_add_f32_e32 v0, 1.0, v0
	v_mul_f32_e32 v0, v1, v0
	v_cvt_pk_bf16_f32 v3, v0, s0
	v_add_f32_e32 v0, 1.0, v2
	v_rcp_f32_e32 v2, v0
	v_add_co_u32_e32 v0, vcc, s16, v124
	s_nop 1
	v_addc_co_u32_e32 v1, vcc, 0, v125, vcc
	global_store_short v[0:1], v3, off offset:1024
	v_fma_f32 v0, v2, -2.0, 1.0
	v_mul_f32_e32 v2, 0x3d372713, v9
	v_mul_f32_e32 v2, v9, v2
	v_fma_f32 v2, v9, v2, v9
	v_mul_f32_e32 v2, 0x3f4c422a, v2
	v_add_f32_e32 v2, v2, v2
	v_mul_f32_e32 v2, 0x3fb8aa3b, v2
	v_exp_f32_e32 v2, v2
	v_mul_f32_e32 v1, 0.5, v8
	v_add_f32_e32 v0, 1.0, v0
	v_mul_f32_e32 v0, v1, v0
	v_cvt_pk_bf16_f32 v3, v0, s0
	v_add_f32_e32 v0, 1.0, v2
	v_rcp_f32_e32 v2, v0
	v_add_co_u32_e32 v0, vcc, s17, v124
	s_nop 1
	v_addc_co_u32_e32 v1, vcc, 0, v125, vcc
	global_store_short v[0:1], v3, off offset:1024
	v_fma_f32 v0, v2, -2.0, 1.0
	v_mul_f32_e32 v2, 0x3d372713, v10
	v_mul_f32_e32 v2, v10, v2
	v_fma_f32 v2, v10, v2, v10
	v_mul_f32_e32 v2, 0x3f4c422a, v2
	v_add_f32_e32 v2, v2, v2
	v_mul_f32_e32 v2, 0x3fb8aa3b, v2
	v_exp_f32_e32 v2, v2
	v_mul_f32_e32 v1, 0.5, v9
	v_add_f32_e32 v0, 1.0, v0
	v_mul_f32_e32 v0, v1, v0
	v_cvt_pk_bf16_f32 v3, v0, s0
	v_add_f32_e32 v0, 1.0, v2
	v_rcp_f32_e32 v2, v0
	v_add_co_u32_e32 v0, vcc, s18, v124
	s_nop 1
	v_addc_co_u32_e32 v1, vcc, 0, v125, vcc
	global_store_short v[0:1], v3, off offset:1024
	v_fma_f32 v0, v2, -2.0, 1.0
	v_mul_f32_e32 v2, 0x3d372713, v11
	v_mul_f32_e32 v2, v11, v2
	v_fma_f32 v2, v11, v2, v11
	v_mul_f32_e32 v2, 0x3f4c422a, v2
	v_add_f32_e32 v2, v2, v2
	v_mul_f32_e32 v2, 0x3fb8aa3b, v2
	v_exp_f32_e32 v2, v2
	v_mul_f32_e32 v1, 0.5, v10
	v_add_f32_e32 v0, 1.0, v0
	v_mul_f32_e32 v0, v1, v0
	v_cvt_pk_bf16_f32 v3, v0, s0
	v_add_f32_e32 v0, 1.0, v2
	v_rcp_f32_e32 v2, v0
	v_add_co_u32_e32 v0, vcc, s19, v124
	s_nop 1
	v_addc_co_u32_e32 v1, vcc, 0, v125, vcc
	global_store_short v[0:1], v3, off offset:1024
	v_fma_f32 v0, v2, -2.0, 1.0
	v_mul_f32_e32 v2, 0x3d372713, v12
	v_mul_f32_e32 v2, v12, v2
	v_fma_f32 v2, v12, v2, v12
	v_mul_f32_e32 v2, 0x3f4c422a, v2
	v_add_f32_e32 v2, v2, v2
	v_mul_f32_e32 v2, 0x3fb8aa3b, v2
	v_exp_f32_e32 v2, v2
	v_mul_f32_e32 v1, 0.5, v11
	v_add_f32_e32 v0, 1.0, v0
	v_mul_f32_e32 v0, v1, v0
	v_cvt_pk_bf16_f32 v3, v0, s0
	v_add_f32_e32 v0, 1.0, v2
	v_rcp_f32_e32 v2, v0
	v_add_co_u32_e32 v0, vcc, s20, v124
	s_nop 1
	v_addc_co_u32_e32 v1, vcc, 0, v125, vcc
	global_store_short v[0:1], v3, off offset:1024
	v_fma_f32 v0, v2, -2.0, 1.0
	v_mul_f32_e32 v2, 0x3d372713, v13
	v_mul_f32_e32 v2, v13, v2
	v_fma_f32 v2, v13, v2, v13
	v_mul_f32_e32 v2, 0x3f4c422a, v2
	v_add_f32_e32 v2, v2, v2
	v_mul_f32_e32 v2, 0x3fb8aa3b, v2
	v_exp_f32_e32 v2, v2
	v_mul_f32_e32 v1, 0.5, v12
	v_add_f32_e32 v0, 1.0, v0
	v_mul_f32_e32 v0, v1, v0
	v_cvt_pk_bf16_f32 v3, v0, s0
	v_add_f32_e32 v0, 1.0, v2
	v_rcp_f32_e32 v2, v0
	v_add_co_u32_e32 v0, vcc, s21, v124
	s_nop 1
	v_addc_co_u32_e32 v1, vcc, 0, v125, vcc
	global_store_short v[0:1], v3, off offset:1024
	v_fma_f32 v0, v2, -2.0, 1.0
	v_mul_f32_e32 v2, 0x3d372713, v14
	v_mul_f32_e32 v2, v14, v2
; __device__ __forceinline__ unsigned f2bf(float f) { return cvtpk(f, 0.f); }
; __device__ __forceinline__ float gelu_tanh(float x) { const float u = 0.7978845608028654f * (x + 0.044715f * x * x * x); const float th = 1.0f - 2.0f * __builtin_amdgcn_rcpf(__expf(2.0f * u) + 1.0f); return 0.5f * x * (1.0f + th); }
; __device__ __forceinline__ int crow16(int g, int hh) { return (g & 3) + 8 * (g >> 2) + 4 * hh; }
; __device__ __forceinline__ void ssm_v2(const KA& A, const Ctx& F, int l, int b, int g) {
;     ...
; #pragma unroll
;     for (int nt = 0; nt < 8; ++nt) if (sp_ & 4) {
;         f32x16 acc = {};
;         const bf16* tp = TM + (size_t)(nt * 16 * 64 + lane) * 8; const bf16* hp = HM + (size_t)(nt * 8 * 64 + lane) * 8;
;         { bf16x8_t tf[16], hf[8];
; #pragma unroll
;           for (int s = 0; s < 16; ++s) if (s <= 2 * nt + 1) tf[s] = *(const bf16x8_t*)(tp + s * 512);
; #pragma unroll
;           for (int s = 0; s < 8; ++s) hf[s] = *(const bf16x8_t*)(hp + s * 512);
; #pragma unroll
;           for (int s = 0; s < 16; ++s) if (s <= 2 * nt + 1) asm volatile("" :: "v"(tf[s]));
;           asm volatile("" :: "v"(hf[0]), "v"(hf[1]), "v"(hf[2]), "v"(hf[3]), "v"(hf[4]), "v"(hf[5]), "v"(hf[6]), "v"(hf[7]));
; #pragma unroll
;           for (int s = 0; s < 16; ++s) if (s <= 2 * nt + 1) acc = __builtin_amdgcn_mfma_f32_32x32x16_bf16(uf[s], tf[s], acc, 0, 0, 0);
; #pragma unroll
;           for (int s = 0; s < 8; ++s) acc = __builtin_amdgcn_mfma_f32_32x32x16_bf16(xf[s], hf[s], acc, 0, 0, 0); }
;         bf16* op = PS + (tok0 + 2 * nt + (r32 >> 4)) * PSW + C_SSM + 16 * g + (r32 & 15);
; #pragma unroll
;         for (int q = 0; q < 16; ++q) { const bf16 gv_ = (bf16)f2bf(gelu_tanh(acc[q])); if (!(F.dry && (DRY_SEL & 2))) op[(size_t)(16 * crow16(q, hh)) * PSW] = gv_; }
	v_fma_f32 v2, v14, v2, v14
	v_mul_f32_e32 v2, 0x3f4c422a, v2
	v_add_f32_e32 v2, v2, v2
	v_mul_f32_e32 v2, 0x3fb8aa3b, v2
	v_exp_f32_e32 v2, v2
	v_mul_f32_e32 v1, 0.5, v13
	v_add_f32_e32 v0, 1.0, v0
	v_mul_f32_e32 v0, v1, v0
	v_cvt_pk_bf16_f32 v3, v0, s0
	v_add_f32_e32 v0, 1.0, v2
	v_rcp_f32_e32 v2, v0
	v_add_co_u32_e32 v0, vcc, s22, v124
	s_nop 1
	v_addc_co_u32_e32 v1, vcc, 0, v125, vcc
	global_store_short v[0:1], v3, off offset:1024
	v_fma_f32 v0, v2, -2.0, 1.0
	v_mul_f32_e32 v2, 0x3d372713, v15
	v_mul_f32_e32 v2, v15, v2
	v_fma_f32 v2, v15, v2, v15
	v_mul_f32_e32 v2, 0x3f4c422a, v2
	v_add_f32_e32 v2, v2, v2
	v_mul_f32_e32 v2, 0x3fb8aa3b, v2
	v_exp_f32_e32 v2, v2
	v_mul_f32_e32 v1, 0.5, v14
	v_add_f32_e32 v0, 1.0, v0
	v_mul_f32_e32 v0, v1, v0
	v_cvt_pk_bf16_f32 v3, v0, s0
	v_add_f32_e32 v0, 1.0, v2
	v_rcp_f32_e32 v2, v0
	v_add_co_u32_e32 v0, vcc, s23, v124
	s_nop 1
	v_addc_co_u32_e32 v1, vcc, 0, v125, vcc
	global_store_short v[0:1], v3, off offset:1024
	v_fma_f32 v0, v2, -2.0, 1.0
	v_mul_f32_e32 v1, 0.5, v15
	v_add_f32_e32 v0, 1.0, v0
	v_mul_f32_e32 v0, v1, v0
	v_cvt_pk_bf16_f32 v2, v0, s0
	v_add_co_u32_e32 v0, vcc, s30, v124
	v_or_b32_e32 v124, 0xc000, v80
	s_nop 0
	v_addc_co_u32_e32 v1, vcc, 0, v125, vcc
	global_store_short v[0:1], v2, off offset:1024
	global_load_dwordx4 v[132:135], v124, s[4:5]
	global_load_dwordx4 v[136:139], v124, s[4:5] offset:1024
	global_load_dwordx4 v[144:147], v124, s[4:5] offset:2048
	global_load_dwordx4 v[148:151], v124, s[4:5] offset:3072
	v_add_co_u32_e32 v126, vcc, s8, v122
	v_mov_b32_e32 v125, v81
	s_nop 0
	v_addc_co_u32_e32 v127, vcc, 0, v123, vcc
	v_lshl_add_u64 v[152:153], s[4:5], 0, v[124:125]
	v_add_co_u32_e32 v168, vcc, s66, v152
	global_load_dwordx4 v[140:143], v[126:127], off offset:3072
	s_nop 0
	v_addc_co_u32_e32 v169, vcc, 0, v153, vcc
	global_load_dwordx4 v[152:155], v[168:169], off
	global_load_dwordx4 v[160:163], v[168:169], off offset:1024
	global_load_dwordx4 v[164:167], v[168:169], off offset:2048
	s_movk_i32 s8, 0x7000
	v_add_co_u32_e32 v180, vcc, s8, v122
	global_load_dwordx4 v[168:171], v[168:169], off offset:3072
	s_nop 0
	v_addc_co_u32_e32 v181, vcc, 0, v123, vcc
	global_load_dwordx4 v[156:159], v[180:181], off offset:-4096
	global_load_dwordx4 v[172:175], v[126:127], off offset:1024
	global_load_dwordx4 v[176:179], v[126:127], off offset:2048
	s_waitcnt vmcnt(11)
	v_mfma_f32_32x32x16_bf16 v[0:15], v[20:23], v[132:135], 0
	global_load_dwordx4 v[184:187], v[180:181], off
	global_load_dwordx4 v[188:191], v[180:181], off offset:1024
	global_load_dwordx4 v[192:195], v[180:181], off offset:2048
	global_load_dwordx4 v[196:199], v[180:181], off offset:3072
	s_waitcnt vmcnt(14)
	s_waitcnt vmcnt(13)
	v_mfma_f32_32x32x16_bf16 v[0:15], v[24:27], v[136:139], v[0:15]
	s_waitcnt vmcnt(12)
	s_waitcnt vmcnt(10)
	s_waitcnt vmcnt(9)
	s_waitcnt vmcnt(8)
	s_waitcnt vmcnt(7)
	s_waitcnt vmcnt(0)
	v_lshl_add_u64 v[180:181], s[2:3], 0, v[128:129]
	v_mfma_f32_32x32x16_bf16 v[0:15], v[28:31], v[144:147], v[0:15]
	v_mfma_f32_32x32x16_bf16 v[0:15], v[16:19], v[148:151], v[0:15]
	v_mfma_f32_32x32x16_bf16 v[0:15], v[32:35], v[152:155], v[0:15]
	v_mfma_f32_32x32x16_bf16 v[0:15], v[36:39], v[160:163], v[0:15]
	v_mfma_f32_32x32x16_bf16 v[0:15], v[52:55], v[164:167], v[0:15]
	v_mfma_f32_32x32x16_bf16 v[0:15], v[48:51], v[168:171], v[0:15]
	v_mfma_f32_32x32x16_bf16 v[0:15], v[82:85], v[156:159], v[0:15]
	v_mfma_f32_32x32x16_bf16 v[0:15], v[86:89], v[172:175], v[0:15]
	v_mfma_f32_32x32x16_bf16 v[0:15], v[90:93], v[176:179], v[0:15]
	v_mfma_f32_32x32x16_bf16 v[0:15], v[94:97], v[140:143], v[0:15]
	v_mfma_f32_32x32x16_bf16 v[0:15], v[98:101], v[184:187], v[0:15]
	v_mfma_f32_32x32x16_bf16 v[0:15], v[102:105], v[188:191], v[0:15]
	v_mfma_f32_32x32x16_bf16 v[0:15], v[110:113], v[192:195], v[0:15]
	v_mfma_f32_32x32x16_bf16 v[0:15], v[106:109], v[196:199], v[0:15]
	s_nop 11
	v_mul_f32_e32 v126, 0x3d372713, v0
	v_mul_f32_e32 v126, v0, v126
	v_fma_f32 v126, v0, v126, v0
	v_mul_f32_e32 v126, 0x3f4c422a, v126
	v_add_f32_e32 v126, v126, v126
	v_mul_f32_e32 v126, 0x3fb8aa3b, v126
	v_exp_f32_e32 v131, v126
	v_mul_f32_e32 v132, 0x3d372713, v1
	v_mul_f32_e32 v132, v1, v132
	v_fma_f32 v132, v1, v132, v1
	v_add_f32_e32 v131, 1.0, v131
	v_mul_f32_e32 v132, 0x3f4c422a, v132
	v_rcp_f32_e32 v131, v131
	v_add_f32_e32 v132, v132, v132
	v_mul_f32_e32 v132, 0x3fb8aa3b, v132
	v_exp_f32_e32 v132, v132
	v_or_b32_e32 v126, 6, v115
	v_mad_u64_u32 v[126:127], s[8:9], v126, s92, v[116:117]
	v_fma_f32 v131, v131, -2.0, 1.0
	v_mad_i32_i24 v127, s7, v236, v127
	v_mul_f32_e32 v0, 0.5, v0
	v_add_f32_e32 v131, 1.0, v131
	v_lshl_add_u64 v[126:127], v[126:127], 0, s[0:1]
	v_mul_f32_e32 v0, v0, v131
	v_add_f32_e32 v131, 1.0, v132
	v_lshl_add_u64 v[126:127], v[126:127], 0, v[120:121]
	v_rcp_f32_e32 v131, v131
	v_lshl_add_u64 v[126:127], v[126:127], 0, v[118:119]
	v_add_co_u32_e32 v132, vcc, s66, v126
	v_cvt_pk_bf16_f32 v0, v0, s0
	s_nop 0
	v_addc_co_u32_e32 v133, vcc, 0, v127, vcc
	global_store_short v[132:133], v0, off offset:1024
	v_fma_f32 v0, v131, -2.0, 1.0
	v_mul_f32_e32 v131, 0x3d372713, v2
	v_mul_f32_e32 v131, v2, v131
	v_fma_f32 v131, v2, v131, v2
	v_mul_f32_e32 v131, 0x3f4c422a, v131
	v_add_f32_e32 v131, v131, v131
	v_mul_f32_e32 v131, 0x3fb8aa3b, v131
	v_exp_f32_e32 v131, v131
	v_mul_f32_e32 v1, 0.5, v1
	v_add_f32_e32 v0, 1.0, v0
	v_mul_f32_e32 v0, v1, v0
	v_cvt_pk_bf16_f32 v132, v0, s0
	v_add_f32_e32 v0, 1.0, v131
	v_rcp_f32_e32 v131, v0
	v_add_co_u32_e32 v0, vcc, s10, v126
	s_nop 1
	v_addc_co_u32_e32 v1, vcc, 0, v127, vcc
	global_store_short v[0:1], v132, off offset:1024
	v_mul_f32_e32 v1, 0.5, v2
	v_mul_f32_e32 v2, 0x3d372713, v3
; __device__ __forceinline__ unsigned f2bf(float f) { return cvtpk(f, 0.f); }
; __device__ __forceinline__ float gelu_tanh(float x) { const float u = 0.7978845608028654f * (x + 0.044715f * x * x * x); const float th = 1.0f - 2.0f * __builtin_amdgcn_rcpf(__expf(2.0f * u) + 1.0f); return 0.5f * x * (1.0f + th); }
; __device__ __forceinline__ int crow16(int g, int hh) { return (g & 3) + 8 * (g >> 2) + 4 * hh; }
; __device__ __forceinline__ void ssm_v2(const KA& A, const Ctx& F, int l, int b, int g) {
;     ...
;         bf16* op = PS + (tok0 + 2 * nt + (r32 >> 4)) * PSW + C_SSM + 16 * g + (r32 & 15);
; #pragma unroll
;         for (int q = 0; q < 16; ++q) { const bf16 gv_ = (bf16)f2bf(gelu_tanh(acc[q])); if (!(F.dry && (DRY_SEL & 2))) op[(size_t)(16 * crow16(q, hh)) * PSW] = gv_; }
	v_mul_f32_e32 v2, v3, v2
	v_fma_f32 v2, v3, v2, v3
	v_mul_f32_e32 v2, 0x3f4c422a, v2
	v_add_f32_e32 v2, v2, v2
	v_mul_f32_e32 v2, 0x3fb8aa3b, v2
	v_exp_f32_e32 v2, v2
	v_fma_f32 v0, v131, -2.0, 1.0
	v_add_f32_e32 v0, 1.0, v0
	v_mul_f32_e32 v0, v1, v0
	v_cvt_pk_bf16_f32 v131, v0, s0
	v_add_f32_e32 v0, 1.0, v2
	v_rcp_f32_e32 v2, v0
	v_add_co_u32_e32 v0, vcc, s11, v126
	s_nop 1
	v_addc_co_u32_e32 v1, vcc, 0, v127, vcc
	global_store_short v[0:1], v131, off offset:1024
	v_fma_f32 v0, v2, -2.0, 1.0
	v_mul_f32_e32 v2, 0x3d372713, v4
	v_mul_f32_e32 v2, v4, v2
	v_fma_f32 v2, v4, v2, v4
	v_mul_f32_e32 v2, 0x3f4c422a, v2
	v_add_f32_e32 v2, v2, v2
	v_mul_f32_e32 v2, 0x3fb8aa3b, v2
	v_exp_f32_e32 v2, v2
	v_mul_f32_e32 v1, 0.5, v3
	v_add_f32_e32 v0, 1.0, v0
	v_mul_f32_e32 v0, v1, v0
	v_cvt_pk_bf16_f32 v3, v0, s0
	v_add_f32_e32 v0, 1.0, v2
	v_rcp_f32_e32 v2, v0
	v_add_co_u32_e32 v0, vcc, s12, v126
	s_nop 1
	v_addc_co_u32_e32 v1, vcc, 0, v127, vcc
	global_store_short v[0:1], v3, off offset:1024
	v_fma_f32 v0, v2, -2.0, 1.0
	v_mul_f32_e32 v2, 0x3d372713, v5
	v_mul_f32_e32 v2, v5, v2
	v_fma_f32 v2, v5, v2, v5
	v_mul_f32_e32 v2, 0x3f4c422a, v2
	v_add_f32_e32 v2, v2, v2
	v_mul_f32_e32 v2, 0x3fb8aa3b, v2
	v_exp_f32_e32 v2, v2
	v_mul_f32_e32 v1, 0.5, v4
	v_add_f32_e32 v0, 1.0, v0
	v_mul_f32_e32 v0, v1, v0
	v_cvt_pk_bf16_f32 v3, v0, s0
	v_add_f32_e32 v0, 1.0, v2
	v_rcp_f32_e32 v2, v0
	v_add_co_u32_e32 v0, vcc, s13, v126
	s_nop 1
	v_addc_co_u32_e32 v1, vcc, 0, v127, vcc
	global_store_short v[0:1], v3, off offset:1024
	v_fma_f32 v0, v2, -2.0, 1.0
	v_mul_f32_e32 v2, 0x3d372713, v6
	v_mul_f32_e32 v2, v6, v2
	v_fma_f32 v2, v6, v2, v6
	v_mul_f32_e32 v2, 0x3f4c422a, v2
	v_add_f32_e32 v2, v2, v2
	v_mul_f32_e32 v2, 0x3fb8aa3b, v2
	v_exp_f32_e32 v2, v2
	v_mul_f32_e32 v1, 0.5, v5
	v_add_f32_e32 v0, 1.0, v0
	v_mul_f32_e32 v0, v1, v0
	v_cvt_pk_bf16_f32 v3, v0, s0
	v_add_f32_e32 v0, 1.0, v2
	v_rcp_f32_e32 v2, v0
	v_add_co_u32_e32 v0, vcc, s14, v126
	s_nop 1
	v_addc_co_u32_e32 v1, vcc, 0, v127, vcc
	global_store_short v[0:1], v3, off offset:1024
	v_fma_f32 v0, v2, -2.0, 1.0
	v_mul_f32_e32 v2, 0x3d372713, v7
	v_mul_f32_e32 v2, v7, v2
	v_fma_f32 v2, v7, v2, v7
	v_mul_f32_e32 v2, 0x3f4c422a, v2
	v_add_f32_e32 v2, v2, v2
	v_mul_f32_e32 v2, 0x3fb8aa3b, v2
	v_exp_f32_e32 v2, v2
	v_mul_f32_e32 v1, 0.5, v6
	v_add_f32_e32 v0, 1.0, v0
	v_mul_f32_e32 v0, v1, v0
	v_cvt_pk_bf16_f32 v3, v0, s0
	v_add_f32_e32 v0, 1.0, v2
	v_rcp_f32_e32 v2, v0
	v_add_co_u32_e32 v0, vcc, s15, v126
	s_nop 1
	v_addc_co_u32_e32 v1, vcc, 0, v127, vcc
	global_store_short v[0:1], v3, off offset:1024
	v_fma_f32 v0, v2, -2.0, 1.0
	v_mul_f32_e32 v2, 0x3d372713, v8
	v_mul_f32_e32 v2, v8, v2
	v_fma_f32 v2, v8, v2, v8
	v_mul_f32_e32 v2, 0x3f4c422a, v2
	v_add_f32_e32 v2, v2, v2
	v_mul_f32_e32 v2, 0x3fb8aa3b, v2
	v_exp_f32_e32 v2, v2
	v_mul_f32_e32 v1, 0.5, v7
	v_add_f32_e32 v0, 1.0, v0
	v_mul_f32_e32 v0, v1, v0
	v_cvt_pk_bf16_f32 v3, v0, s0
	v_add_f32_e32 v0, 1.0, v2
	v_rcp_f32_e32 v2, v0
	v_add_co_u32_e32 v0, vcc, s16, v126
	s_nop 1
	v_addc_co_u32_e32 v1, vcc, 0, v127, vcc
	global_store_short v[0:1], v3, off offset:1024
	v_fma_f32 v0, v2, -2.0, 1.0
	v_mul_f32_e32 v2, 0x3d372713, v9
	v_mul_f32_e32 v2, v9, v2
	v_fma_f32 v2, v9, v2, v9
	v_mul_f32_e32 v2, 0x3f4c422a, v2
	v_add_f32_e32 v2, v2, v2
	v_mul_f32_e32 v2, 0x3fb8aa3b, v2
	v_exp_f32_e32 v2, v2
	v_mul_f32_e32 v1, 0.5, v8
	v_add_f32_e32 v0, 1.0, v0
	v_mul_f32_e32 v0, v1, v0
	v_cvt_pk_bf16_f32 v3, v0, s0
	v_add_f32_e32 v0, 1.0, v2
	v_rcp_f32_e32 v2, v0
	v_add_co_u32_e32 v0, vcc, s17, v126
	s_nop 1
	v_addc_co_u32_e32 v1, vcc, 0, v127, vcc
	global_store_short v[0:1], v3, off offset:1024
	v_fma_f32 v0, v2, -2.0, 1.0
	v_mul_f32_e32 v2, 0x3d372713, v10
	v_mul_f32_e32 v2, v10, v2
	v_fma_f32 v2, v10, v2, v10
	v_mul_f32_e32 v2, 0x3f4c422a, v2
	v_add_f32_e32 v2, v2, v2
	v_mul_f32_e32 v2, 0x3fb8aa3b, v2
	v_exp_f32_e32 v2, v2
	v_mul_f32_e32 v1, 0.5, v9
	v_add_f32_e32 v0, 1.0, v0
	v_mul_f32_e32 v0, v1, v0
	v_cvt_pk_bf16_f32 v3, v0, s0
	v_add_f32_e32 v0, 1.0, v2
	v_rcp_f32_e32 v2, v0
	v_add_co_u32_e32 v0, vcc, s18, v126
	s_nop 1
	v_addc_co_u32_e32 v1, vcc, 0, v127, vcc
	global_store_short v[0:1], v3, off offset:1024
	v_fma_f32 v0, v2, -2.0, 1.0
	v_mul_f32_e32 v2, 0x3d372713, v11
	v_mul_f32_e32 v2, v11, v2
	v_fma_f32 v2, v11, v2, v11
	v_mul_f32_e32 v2, 0x3f4c422a, v2
	v_add_f32_e32 v2, v2, v2
	v_mul_f32_e32 v2, 0x3fb8aa3b, v2
	v_exp_f32_e32 v2, v2
	v_mul_f32_e32 v1, 0.5, v10
	v_add_f32_e32 v0, 1.0, v0
	v_mul_f32_e32 v0, v1, v0
	v_cvt_pk_bf16_f32 v3, v0, s0
	v_add_f32_e32 v0, 1.0, v2
	v_rcp_f32_e32 v2, v0
	v_add_co_u32_e32 v0, vcc, s19, v126
	s_nop 1
	v_addc_co_u32_e32 v1, vcc, 0, v127, vcc
	global_store_short v[0:1], v3, off offset:1024
	v_fma_f32 v0, v2, -2.0, 1.0
	v_mul_f32_e32 v2, 0x3d372713, v12
	v_mul_f32_e32 v2, v12, v2
	v_fma_f32 v2, v12, v2, v12
	v_mul_f32_e32 v2, 0x3f4c422a, v2
	v_add_f32_e32 v2, v2, v2
	v_mul_f32_e32 v2, 0x3fb8aa3b, v2
	v_exp_f32_e32 v2, v2
	v_mul_f32_e32 v1, 0.5, v11
	v_add_f32_e32 v0, 1.0, v0
	v_mul_f32_e32 v0, v1, v0
	v_cvt_pk_bf16_f32 v3, v0, s0
	v_add_f32_e32 v0, 1.0, v2
	v_rcp_f32_e32 v2, v0
	v_add_co_u32_e32 v0, vcc, s20, v126
	s_nop 1
	v_addc_co_u32_e32 v1, vcc, 0, v127, vcc
	global_store_short v[0:1], v3, off offset:1024
	v_fma_f32 v0, v2, -2.0, 1.0
	v_mul_f32_e32 v2, 0x3d372713, v13
	v_mul_f32_e32 v2, v13, v2
	v_fma_f32 v2, v13, v2, v13
	v_mul_f32_e32 v2, 0x3f4c422a, v2
	v_add_f32_e32 v2, v2, v2
	v_mul_f32_e32 v2, 0x3fb8aa3b, v2
	v_exp_f32_e32 v2, v2
	v_mul_f32_e32 v1, 0.5, v12
	v_add_f32_e32 v0, 1.0, v0
	v_mul_f32_e32 v0, v1, v0
	v_cvt_pk_bf16_f32 v3, v0, s0
	v_add_f32_e32 v0, 1.0, v2
	v_rcp_f32_e32 v2, v0
	v_add_co_u32_e32 v0, vcc, s21, v126
; __device__ __forceinline__ unsigned f2bf(float f) { return cvtpk(f, 0.f); }
; __device__ __forceinline__ float gelu_tanh(float x) { const float u = 0.7978845608028654f * (x + 0.044715f * x * x * x); const float th = 1.0f - 2.0f * __builtin_amdgcn_rcpf(__expf(2.0f * u) + 1.0f); return 0.5f * x * (1.0f + th); }
; __device__ __forceinline__ int crow16(int g, int hh) { return (g & 3) + 8 * (g >> 2) + 4 * hh; }
; __device__ __forceinline__ void ssm_v2(const KA& A, const Ctx& F, int l, int b, int g) {
;     ...
; #pragma unroll
;     for (int nt = 0; nt < 8; ++nt) if (sp_ & 4) {
;         f32x16 acc = {};
;         const bf16* tp = TM + (size_t)(nt * 16 * 64 + lane) * 8; const bf16* hp = HM + (size_t)(nt * 8 * 64 + lane) * 8;
;         { bf16x8_t tf[16], hf[8];
; #pragma unroll
;           for (int s = 0; s < 16; ++s) if (s <= 2 * nt + 1) tf[s] = *(const bf16x8_t*)(tp + s * 512);
; #pragma unroll
;           for (int s = 0; s < 8; ++s) hf[s] = *(const bf16x8_t*)(hp + s * 512);
; #pragma unroll
;           for (int s = 0; s < 16; ++s) if (s <= 2 * nt + 1) asm volatile("" :: "v"(tf[s]));
;           asm volatile("" :: "v"(hf[0]), "v"(hf[1]), "v"(hf[2]), "v"(hf[3]), "v"(hf[4]), "v"(hf[5]), "v"(hf[6]), "v"(hf[7]));
; #pragma unroll
;           for (int s = 0; s < 16; ++s) if (s <= 2 * nt + 1) acc = __builtin_amdgcn_mfma_f32_32x32x16_bf16(uf[s], tf[s], acc, 0, 0, 0);
; #pragma unroll
;           for (int s = 0; s < 8; ++s) acc = __builtin_amdgcn_mfma_f32_32x32x16_bf16(xf[s], hf[s], acc, 0, 0, 0); }
;         bf16* op = PS + (tok0 + 2 * nt + (r32 >> 4)) * PSW + C_SSM + 16 * g + (r32 & 15);
; #pragma unroll
;         for (int q = 0; q < 16; ++q) { const bf16 gv_ = (bf16)f2bf(gelu_tanh(acc[q])); if (!(F.dry && (DRY_SEL & 2))) op[(size_t)(16 * crow16(q, hh)) * PSW] = gv_; }
	s_nop 1
	v_addc_co_u32_e32 v1, vcc, 0, v127, vcc
	global_store_short v[0:1], v3, off offset:1024
	v_fma_f32 v0, v2, -2.0, 1.0
	v_mul_f32_e32 v2, 0x3d372713, v14
	v_mul_f32_e32 v2, v14, v2
	v_fma_f32 v2, v14, v2, v14
	v_mul_f32_e32 v2, 0x3f4c422a, v2
	v_add_f32_e32 v2, v2, v2
	v_mul_f32_e32 v2, 0x3fb8aa3b, v2
	v_exp_f32_e32 v2, v2
	v_mul_f32_e32 v1, 0.5, v13
	v_add_f32_e32 v0, 1.0, v0
	v_mul_f32_e32 v0, v1, v0
	v_cvt_pk_bf16_f32 v3, v0, s0
	v_add_f32_e32 v0, 1.0, v2
	v_rcp_f32_e32 v2, v0
	v_add_co_u32_e32 v0, vcc, s22, v126
	s_nop 1
	v_addc_co_u32_e32 v1, vcc, 0, v127, vcc
	global_store_short v[0:1], v3, off offset:1024
	v_fma_f32 v0, v2, -2.0, 1.0
	v_mul_f32_e32 v2, 0x3d372713, v15
	v_mul_f32_e32 v2, v15, v2
	v_fma_f32 v2, v15, v2, v15
	v_mul_f32_e32 v2, 0x3f4c422a, v2
	v_add_f32_e32 v2, v2, v2
	v_mul_f32_e32 v2, 0x3fb8aa3b, v2
	v_exp_f32_e32 v2, v2
	v_mul_f32_e32 v1, 0.5, v14
	v_add_f32_e32 v0, 1.0, v0
	v_mul_f32_e32 v0, v1, v0
	v_cvt_pk_bf16_f32 v3, v0, s0
	v_add_f32_e32 v0, 1.0, v2
	v_rcp_f32_e32 v2, v0
	v_add_co_u32_e32 v0, vcc, s23, v126
	s_nop 1
	v_addc_co_u32_e32 v1, vcc, 0, v127, vcc
	global_store_short v[0:1], v3, off offset:1024
	v_fma_f32 v0, v2, -2.0, 1.0
	v_mul_f32_e32 v1, 0.5, v15
	v_add_f32_e32 v0, 1.0, v0
	v_mul_f32_e32 v0, v1, v0
	v_cvt_pk_bf16_f32 v2, v0, s0
	v_add_co_u32_e32 v0, vcc, s30, v126
	s_nop 1
	v_addc_co_u32_e32 v1, vcc, 0, v127, vcc
	v_lshl_add_u64 v[126:127], s[4:5], 0, v[80:81]
	s_mov_b32 s4, 0x11000
	v_add_co_u32_e32 v168, vcc, s4, v126
	global_store_short v[0:1], v2, off offset:1024
	s_nop 0
	v_addc_co_u32_e32 v169, vcc, 0, v127, vcc
	global_load_dwordx4 v[132:135], v[168:169], off offset:-4096
	s_mov_b32 s4, 0x10000
	v_add_co_u32_e32 v148, vcc, s4, v126
	s_mov_b32 s4, 0x12000
	s_nop 0
	v_addc_co_u32_e32 v149, vcc, 0, v127, vcc
	global_load_dwordx4 v[136:139], v[148:149], off offset:1024
	global_load_dwordx4 v[140:143], v128, s[2:3] offset:3072
	global_load_dwordx4 v[144:147], v[148:149], off offset:2048
	global_load_dwordx4 v[176:179], v128, s[2:3]
	global_load_dwordx4 v[152:155], v[168:169], off
	global_load_dwordx4 v[160:163], v[168:169], off offset:1024
	global_load_dwordx4 v[164:167], v[168:169], off offset:2048
	v_add_co_u32_e32 v172, vcc, s4, v126
	global_load_dwordx4 v[148:151], v[148:149], off offset:3072
	s_nop 0
	v_addc_co_u32_e32 v173, vcc, 0, v127, vcc
	global_load_dwordx4 v[156:159], v[172:173], off
	s_waitcnt vmcnt(9)
	v_mfma_f32_32x32x16_bf16 v[0:15], v[20:23], v[132:135], 0
	global_load_dwordx4 v[168:171], v[168:169], off offset:3072
	v_add_co_u32_e32 v180, vcc, s66, v180
	global_load_dwordx4 v[172:175], v[172:173], off offset:1024
	s_nop 0
	v_addc_co_u32_e32 v181, vcc, 0, v181, vcc
	global_load_dwordx4 v[184:187], v[180:181], off
	s_waitcnt vmcnt(11)
	v_mfma_f32_32x32x16_bf16 v[0:15], v[24:27], v[136:139], v[0:15]
	global_load_dwordx4 v[188:191], v128, s[2:3] offset:1024
	global_load_dwordx4 v[192:195], v[180:181], off offset:3072
	global_load_dwordx4 v[196:199], v128, s[2:3] offset:2048
	global_load_dwordx4 v[200:203], v[180:181], off offset:1024
	global_load_dwordx4 v[204:207], v[180:181], off offset:2048
	v_or_b32_e32 v128, 8, v115
	v_mad_u64_u32 v[128:129], s[4:5], v128, s92, v[116:117]
	s_waitcnt vmcnt(14)
	v_mfma_f32_32x32x16_bf16 v[0:15], v[28:31], v[144:147], v[0:15]
	v_mad_i32_i24 v129, s7, v236, v129
	v_lshl_add_u64 v[128:129], v[128:129], 0, s[0:1]
	v_lshl_add_u64 v[128:129], v[128:129], 0, v[120:121]
	v_lshl_add_u64 v[128:129], v[128:129], 0, v[118:119]
	v_add_co_u32_e32 v132, vcc, s66, v128
	s_waitcnt vmcnt(9)
	v_mfma_f32_32x32x16_bf16 v[0:15], v[16:19], v[148:151], v[0:15]
	v_addc_co_u32_e32 v133, vcc, 0, v129, vcc
	v_mfma_f32_32x32x16_bf16 v[0:15], v[32:35], v[152:155], v[0:15]
	s_waitcnt vmcnt(7)
	s_waitcnt vmcnt(6)
	s_waitcnt vmcnt(0)
	v_mfma_f32_32x32x16_bf16 v[0:15], v[36:39], v[160:163], v[0:15]
	s_mov_b32 s4, 0x15000
	v_mfma_f32_32x32x16_bf16 v[0:15], v[52:55], v[164:167], v[0:15]
	v_mfma_f32_32x32x16_bf16 v[0:15], v[48:51], v[168:171], v[0:15]
	v_mfma_f32_32x32x16_bf16 v[0:15], v[40:43], v[156:159], v[0:15]
	v_mfma_f32_32x32x16_bf16 v[0:15], v[44:47], v[172:175], v[0:15]
	v_mfma_f32_32x32x16_bf16 v[0:15], v[82:85], v[176:179], v[0:15]
	v_mfma_f32_32x32x16_bf16 v[0:15], v[86:89], v[188:191], v[0:15]
	v_mfma_f32_32x32x16_bf16 v[0:15], v[90:93], v[196:199], v[0:15]
	v_mfma_f32_32x32x16_bf16 v[0:15], v[94:97], v[140:143], v[0:15]
	v_mfma_f32_32x32x16_bf16 v[0:15], v[98:101], v[184:187], v[0:15]
	v_mfma_f32_32x32x16_bf16 v[0:15], v[102:105], v[200:203], v[0:15]
	v_mfma_f32_32x32x16_bf16 v[0:15], v[110:113], v[204:207], v[0:15]
	v_mfma_f32_32x32x16_bf16 v[0:15], v[106:109], v[192:195], v[0:15]
	s_nop 11
	v_mul_f32_e32 v80, 0x3d372713, v0
	v_mul_f32_e32 v80, v0, v80
	v_fma_f32 v80, v0, v80, v0
	v_mul_f32_e32 v80, 0x3f4c422a, v80
	v_add_f32_e32 v80, v80, v80
	v_mul_f32_e32 v80, 0x3fb8aa3b, v80
	v_exp_f32_e32 v80, v80
	v_mul_f32_e32 v131, 0x3d372713, v1
	v_mul_f32_e32 v131, v1, v131
	v_fma_f32 v131, v1, v131, v1
	v_add_f32_e32 v80, 1.0, v80
	v_mul_f32_e32 v131, 0x3f4c422a, v131
	v_rcp_f32_e32 v80, v80
	v_add_f32_e32 v131, v131, v131
	v_mul_f32_e32 v131, 0x3fb8aa3b, v131
	v_exp_f32_e32 v131, v131
	v_fma_f32 v80, v80, -2.0, 1.0
	v_mul_f32_e32 v0, 0.5, v0
	v_add_f32_e32 v80, 1.0, v80
	v_mul_f32_e32 v0, v0, v80
	v_add_f32_e32 v80, 1.0, v131
	v_rcp_f32_e32 v80, v80
	v_cvt_pk_bf16_f32 v0, v0, s0
	global_store_short v[132:133], v0, off offset:1024
	v_mul_f32_e32 v1, 0.5, v1
	v_fma_f32 v0, v80, -2.0, 1.0
	v_mul_f32_e32 v80, 0x3d372713, v2
	v_mul_f32_e32 v80, v2, v80
	v_fma_f32 v80, v2, v80, v2
	v_mul_f32_e32 v80, 0x3f4c422a, v80
	v_add_f32_e32 v80, v80, v80
	v_mul_f32_e32 v80, 0x3fb8aa3b, v80
; __device__ __forceinline__ unsigned f2bf(float f) { return cvtpk(f, 0.f); }
; __device__ __forceinline__ float gelu_tanh(float x) { const float u = 0.7978845608028654f * (x + 0.044715f * x * x * x); const float th = 1.0f - 2.0f * __builtin_amdgcn_rcpf(__expf(2.0f * u) + 1.0f); return 0.5f * x * (1.0f + th); }
; __device__ __forceinline__ int crow16(int g, int hh) { return (g & 3) + 8 * (g >> 2) + 4 * hh; }
; __device__ __forceinline__ void ssm_v2(const KA& A, const Ctx& F, int l, int b, int g) {
;     ...
;         bf16* op = PS + (tok0 + 2 * nt + (r32 >> 4)) * PSW + C_SSM + 16 * g + (r32 & 15);
; #pragma unroll
;         for (int q = 0; q < 16; ++q) { const bf16 gv_ = (bf16)f2bf(gelu_tanh(acc[q])); if (!(F.dry && (DRY_SEL & 2))) op[(size_t)(16 * crow16(q, hh)) * PSW] = gv_; }
	v_exp_f32_e32 v80, v80
	v_add_f32_e32 v0, 1.0, v0
	v_mul_f32_e32 v0, v1, v0
	v_cvt_pk_bf16_f32 v131, v0, s0
	v_add_f32_e32 v0, 1.0, v80
	v_rcp_f32_e32 v80, v0
	v_add_co_u32_e32 v0, vcc, s10, v128
	s_nop 1
	v_addc_co_u32_e32 v1, vcc, 0, v129, vcc
	global_store_short v[0:1], v131, off offset:1024
	v_mul_f32_e32 v1, 0.5, v2
	v_mul_f32_e32 v2, 0x3d372713, v3
	v_mul_f32_e32 v2, v3, v2
	v_fma_f32 v2, v3, v2, v3
	v_mul_f32_e32 v2, 0x3f4c422a, v2
	v_add_f32_e32 v2, v2, v2
	v_mul_f32_e32 v2, 0x3fb8aa3b, v2
	v_exp_f32_e32 v2, v2
	v_fma_f32 v0, v80, -2.0, 1.0
	v_add_f32_e32 v0, 1.0, v0
	v_mul_f32_e32 v0, v1, v0
	v_cvt_pk_bf16_f32 v80, v0, s0
	v_add_f32_e32 v0, 1.0, v2
	v_rcp_f32_e32 v2, v0
	v_add_co_u32_e32 v0, vcc, s11, v128
	s_nop 1
	v_addc_co_u32_e32 v1, vcc, 0, v129, vcc
	global_store_short v[0:1], v80, off offset:1024
	v_fma_f32 v0, v2, -2.0, 1.0
	v_mul_f32_e32 v2, 0x3d372713, v4
	v_mul_f32_e32 v2, v4, v2
	v_fma_f32 v2, v4, v2, v4
	v_mul_f32_e32 v2, 0x3f4c422a, v2
	v_add_f32_e32 v2, v2, v2
	v_mul_f32_e32 v2, 0x3fb8aa3b, v2
	v_exp_f32_e32 v2, v2
	v_mul_f32_e32 v1, 0.5, v3
	v_add_f32_e32 v0, 1.0, v0
	v_mul_f32_e32 v0, v1, v0
	v_cvt_pk_bf16_f32 v3, v0, s0
	v_add_f32_e32 v0, 1.0, v2
	v_rcp_f32_e32 v2, v0
	v_add_co_u32_e32 v0, vcc, s12, v128
	s_nop 1
	v_addc_co_u32_e32 v1, vcc, 0, v129, vcc
	global_store_short v[0:1], v3, off offset:1024
	v_fma_f32 v0, v2, -2.0, 1.0
	v_mul_f32_e32 v2, 0x3d372713, v5
	v_mul_f32_e32 v2, v5, v2
	v_fma_f32 v2, v5, v2, v5
	v_mul_f32_e32 v2, 0x3f4c422a, v2
	v_add_f32_e32 v2, v2, v2
	v_mul_f32_e32 v2, 0x3fb8aa3b, v2
	v_exp_f32_e32 v2, v2
	v_mul_f32_e32 v1, 0.5, v4
	v_add_f32_e32 v0, 1.0, v0
	v_mul_f32_e32 v0, v1, v0
	v_cvt_pk_bf16_f32 v3, v0, s0
	v_add_f32_e32 v0, 1.0, v2
	v_rcp_f32_e32 v2, v0
	v_add_co_u32_e32 v0, vcc, s13, v128
	s_nop 1
	v_addc_co_u32_e32 v1, vcc, 0, v129, vcc
	global_store_short v[0:1], v3, off offset:1024
	v_fma_f32 v0, v2, -2.0, 1.0
	v_mul_f32_e32 v2, 0x3d372713, v6
	v_mul_f32_e32 v2, v6, v2
	v_fma_f32 v2, v6, v2, v6
	v_mul_f32_e32 v2, 0x3f4c422a, v2
	v_add_f32_e32 v2, v2, v2
	v_mul_f32_e32 v2, 0x3fb8aa3b, v2
	v_exp_f32_e32 v2, v2
	v_mul_f32_e32 v1, 0.5, v5
	v_add_f32_e32 v0, 1.0, v0
	v_mul_f32_e32 v0, v1, v0
	v_cvt_pk_bf16_f32 v3, v0, s0
	v_add_f32_e32 v0, 1.0, v2
	v_rcp_f32_e32 v2, v0
	v_add_co_u32_e32 v0, vcc, s14, v128
	s_nop 1
	v_addc_co_u32_e32 v1, vcc, 0, v129, vcc
	global_store_short v[0:1], v3, off offset:1024
	v_fma_f32 v0, v2, -2.0, 1.0
	v_mul_f32_e32 v2, 0x3d372713, v7
	v_mul_f32_e32 v2, v7, v2
	v_fma_f32 v2, v7, v2, v7
	v_mul_f32_e32 v2, 0x3f4c422a, v2
	v_add_f32_e32 v2, v2, v2
	v_mul_f32_e32 v2, 0x3fb8aa3b, v2
	v_exp_f32_e32 v2, v2
	v_mul_f32_e32 v1, 0.5, v6
	v_add_f32_e32 v0, 1.0, v0
	v_mul_f32_e32 v0, v1, v0
	v_cvt_pk_bf16_f32 v3, v0, s0
	v_add_f32_e32 v0, 1.0, v2
	v_rcp_f32_e32 v2, v0
	v_add_co_u32_e32 v0, vcc, s15, v128
	s_nop 1
	v_addc_co_u32_e32 v1, vcc, 0, v129, vcc
	global_store_short v[0:1], v3, off offset:1024
	v_fma_f32 v0, v2, -2.0, 1.0
	v_mul_f32_e32 v2, 0x3d372713, v8
	v_mul_f32_e32 v2, v8, v2
	v_fma_f32 v2, v8, v2, v8
	v_mul_f32_e32 v2, 0x3f4c422a, v2
	v_add_f32_e32 v2, v2, v2
	v_mul_f32_e32 v2, 0x3fb8aa3b, v2
	v_exp_f32_e32 v2, v2
	v_mul_f32_e32 v1, 0.5, v7
	v_add_f32_e32 v0, 1.0, v0
	v_mul_f32_e32 v0, v1, v0
	v_cvt_pk_bf16_f32 v3, v0, s0
	v_add_f32_e32 v0, 1.0, v2
	v_rcp_f32_e32 v2, v0
	v_add_co_u32_e32 v0, vcc, s16, v128
	s_nop 1
	v_addc_co_u32_e32 v1, vcc, 0, v129, vcc
	global_store_short v[0:1], v3, off offset:1024
	v_fma_f32 v0, v2, -2.0, 1.0
	v_mul_f32_e32 v2, 0x3d372713, v9
	v_mul_f32_e32 v2, v9, v2
	v_fma_f32 v2, v9, v2, v9
	v_mul_f32_e32 v2, 0x3f4c422a, v2
	v_add_f32_e32 v2, v2, v2
	v_mul_f32_e32 v2, 0x3fb8aa3b, v2
	v_exp_f32_e32 v2, v2
	v_mul_f32_e32 v1, 0.5, v8
	v_add_f32_e32 v0, 1.0, v0
	v_mul_f32_e32 v0, v1, v0
	v_cvt_pk_bf16_f32 v3, v0, s0
	v_add_f32_e32 v0, 1.0, v2
	v_rcp_f32_e32 v2, v0
	v_add_co_u32_e32 v0, vcc, s17, v128
	s_nop 1
	v_addc_co_u32_e32 v1, vcc, 0, v129, vcc
	global_store_short v[0:1], v3, off offset:1024
	v_fma_f32 v0, v2, -2.0, 1.0
	v_mul_f32_e32 v2, 0x3d372713, v10
	v_mul_f32_e32 v2, v10, v2
	v_fma_f32 v2, v10, v2, v10
	v_mul_f32_e32 v2, 0x3f4c422a, v2
	v_add_f32_e32 v2, v2, v2
	v_mul_f32_e32 v2, 0x3fb8aa3b, v2
	v_exp_f32_e32 v2, v2
	v_mul_f32_e32 v1, 0.5, v9
	v_add_f32_e32 v0, 1.0, v0
	v_mul_f32_e32 v0, v1, v0
	v_cvt_pk_bf16_f32 v3, v0, s0
	v_add_f32_e32 v0, 1.0, v2
	v_rcp_f32_e32 v2, v0
	v_add_co_u32_e32 v0, vcc, s18, v128
	s_nop 1
	v_addc_co_u32_e32 v1, vcc, 0, v129, vcc
	global_store_short v[0:1], v3, off offset:1024
	v_fma_f32 v0, v2, -2.0, 1.0
	v_mul_f32_e32 v2, 0x3d372713, v11
	v_mul_f32_e32 v2, v11, v2
	v_fma_f32 v2, v11, v2, v11
	v_mul_f32_e32 v2, 0x3f4c422a, v2
	v_add_f32_e32 v2, v2, v2
	v_mul_f32_e32 v2, 0x3fb8aa3b, v2
	v_exp_f32_e32 v2, v2
	v_mul_f32_e32 v1, 0.5, v10
	v_add_f32_e32 v0, 1.0, v0
	v_mul_f32_e32 v0, v1, v0
	v_cvt_pk_bf16_f32 v3, v0, s0
	v_add_f32_e32 v0, 1.0, v2
	v_rcp_f32_e32 v2, v0
	v_add_co_u32_e32 v0, vcc, s19, v128
	s_nop 1
	v_addc_co_u32_e32 v1, vcc, 0, v129, vcc
	global_store_short v[0:1], v3, off offset:1024
	v_fma_f32 v0, v2, -2.0, 1.0
	v_mul_f32_e32 v2, 0x3d372713, v12
	v_mul_f32_e32 v2, v12, v2
	v_fma_f32 v2, v12, v2, v12
	v_mul_f32_e32 v2, 0x3f4c422a, v2
	v_add_f32_e32 v2, v2, v2
	v_mul_f32_e32 v2, 0x3fb8aa3b, v2
	v_exp_f32_e32 v2, v2
	v_mul_f32_e32 v1, 0.5, v11
	v_add_f32_e32 v0, 1.0, v0
	v_mul_f32_e32 v0, v1, v0
	v_cvt_pk_bf16_f32 v3, v0, s0
	v_add_f32_e32 v0, 1.0, v2
	v_rcp_f32_e32 v2, v0
	v_add_co_u32_e32 v0, vcc, s20, v128
	s_nop 1
	v_addc_co_u32_e32 v1, vcc, 0, v129, vcc
	global_store_short v[0:1], v3, off offset:1024
	v_fma_f32 v0, v2, -2.0, 1.0
	v_mul_f32_e32 v2, 0x3d372713, v13
; __device__ __forceinline__ unsigned f2bf(float f) { return cvtpk(f, 0.f); }
; __device__ __forceinline__ float gelu_tanh(float x) { const float u = 0.7978845608028654f * (x + 0.044715f * x * x * x); const float th = 1.0f - 2.0f * __builtin_amdgcn_rcpf(__expf(2.0f * u) + 1.0f); return 0.5f * x * (1.0f + th); }
; __device__ __forceinline__ int crow16(int g, int hh) { return (g & 3) + 8 * (g >> 2) + 4 * hh; }
; __device__ __forceinline__ void ssm_v2(const KA& A, const Ctx& F, int l, int b, int g) {
;     ...
;     for (int nt = 0; nt < 8; ++nt) if (sp_ & 4) {
;         f32x16 acc = {};
;         const bf16* tp = TM + (size_t)(nt * 16 * 64 + lane) * 8; const bf16* hp = HM + (size_t)(nt * 8 * 64 + lane) * 8;
;         { bf16x8_t tf[16], hf[8];
; #pragma unroll
;           for (int s = 0; s < 16; ++s) if (s <= 2 * nt + 1) tf[s] = *(const bf16x8_t*)(tp + s * 512);
; #pragma unroll
;           for (int s = 0; s < 8; ++s) hf[s] = *(const bf16x8_t*)(hp + s * 512);
; #pragma unroll
;           for (int s = 0; s < 16; ++s) if (s <= 2 * nt + 1) asm volatile("" :: "v"(tf[s]));
;           asm volatile("" :: "v"(hf[0]), "v"(hf[1]), "v"(hf[2]), "v"(hf[3]), "v"(hf[4]), "v"(hf[5]), "v"(hf[6]), "v"(hf[7]));
; #pragma unroll
;           for (int s = 0; s < 16; ++s) if (s <= 2 * nt + 1) acc = __builtin_amdgcn_mfma_f32_32x32x16_bf16(uf[s], tf[s], acc, 0, 0, 0);
; #pragma unroll
;           for (int s = 0; s < 8; ++s) acc = __builtin_amdgcn_mfma_f32_32x32x16_bf16(xf[s], hf[s], acc, 0, 0, 0); }
;         bf16* op = PS + (tok0 + 2 * nt + (r32 >> 4)) * PSW + C_SSM + 16 * g + (r32 & 15);
; #pragma unroll
;         for (int q = 0; q < 16; ++q) { const bf16 gv_ = (bf16)f2bf(gelu_tanh(acc[q])); if (!(F.dry && (DRY_SEL & 2))) op[(size_t)(16 * crow16(q, hh)) * PSW] = gv_; }
	v_mul_f32_e32 v2, v13, v2
	v_fma_f32 v2, v13, v2, v13
	v_mul_f32_e32 v2, 0x3f4c422a, v2
	v_add_f32_e32 v2, v2, v2
	v_mul_f32_e32 v2, 0x3fb8aa3b, v2
	v_exp_f32_e32 v2, v2
	v_mul_f32_e32 v1, 0.5, v12
	v_add_f32_e32 v0, 1.0, v0
	v_mul_f32_e32 v0, v1, v0
	v_cvt_pk_bf16_f32 v3, v0, s0
	v_add_f32_e32 v0, 1.0, v2
	v_rcp_f32_e32 v2, v0
	v_add_co_u32_e32 v0, vcc, s21, v128
	s_nop 1
	v_addc_co_u32_e32 v1, vcc, 0, v129, vcc
	global_store_short v[0:1], v3, off offset:1024
	v_fma_f32 v0, v2, -2.0, 1.0
	v_mul_f32_e32 v2, 0x3d372713, v14
	v_mul_f32_e32 v2, v14, v2
	v_fma_f32 v2, v14, v2, v14
	v_mul_f32_e32 v2, 0x3f4c422a, v2
	v_add_f32_e32 v2, v2, v2
	v_mul_f32_e32 v2, 0x3fb8aa3b, v2
	v_exp_f32_e32 v2, v2
	v_mul_f32_e32 v1, 0.5, v13
	v_add_f32_e32 v0, 1.0, v0
	v_mul_f32_e32 v0, v1, v0
	v_cvt_pk_bf16_f32 v3, v0, s0
	v_add_f32_e32 v0, 1.0, v2
	v_rcp_f32_e32 v2, v0
	v_add_co_u32_e32 v0, vcc, s22, v128
	s_nop 1
	v_addc_co_u32_e32 v1, vcc, 0, v129, vcc
	global_store_short v[0:1], v3, off offset:1024
	v_fma_f32 v0, v2, -2.0, 1.0
	v_mul_f32_e32 v2, 0x3d372713, v15
	v_mul_f32_e32 v2, v15, v2
	v_fma_f32 v2, v15, v2, v15
	v_mul_f32_e32 v2, 0x3f4c422a, v2
	v_add_f32_e32 v2, v2, v2
	v_mul_f32_e32 v2, 0x3fb8aa3b, v2
	v_exp_f32_e32 v2, v2
	v_mul_f32_e32 v1, 0.5, v14
	v_add_f32_e32 v0, 1.0, v0
	v_mul_f32_e32 v0, v1, v0
	v_cvt_pk_bf16_f32 v3, v0, s0
	v_add_f32_e32 v0, 1.0, v2
	v_rcp_f32_e32 v2, v0
	v_add_co_u32_e32 v0, vcc, s23, v128
	s_nop 1
	v_addc_co_u32_e32 v1, vcc, 0, v129, vcc
	global_store_short v[0:1], v3, off offset:1024
	v_fma_f32 v0, v2, -2.0, 1.0
	v_mul_f32_e32 v1, 0.5, v15
	v_add_f32_e32 v0, 1.0, v0
	v_mul_f32_e32 v0, v1, v0
	v_cvt_pk_bf16_f32 v2, v0, s0
	v_add_co_u32_e32 v0, vcc, s30, v128
	s_nop 1
	v_addc_co_u32_e32 v1, vcc, 0, v129, vcc
	v_add_co_u32_e32 v128, vcc, s4, v126
	global_store_short v[0:1], v2, off offset:1024
	s_nop 0
	v_addc_co_u32_e32 v129, vcc, 0, v127, vcc
	global_load_dwordx4 v[132:135], v[128:129], off offset:-4096
	s_mov_b32 s4, 0x14000
	v_add_co_u32_e32 v148, vcc, s4, v126
	s_mov_b32 s4, 0x16000
	s_nop 0
	v_addc_co_u32_e32 v149, vcc, 0, v127, vcc
	global_load_dwordx4 v[136:139], v[148:149], off offset:1024
	global_load_dwordx4 v[140:143], v[128:129], off
	global_load_dwordx4 v[144:147], v[148:149], off offset:2048
	global_load_dwordx4 v[164:167], v[128:129], off offset:3072
	global_load_dwordx4 v[156:159], v[128:129], off offset:1024
	global_load_dwordx4 v[160:163], v[128:129], off offset:2048
	v_add_co_u32_e32 v180, vcc, s4, v126
	global_load_dwordx4 v[148:151], v[148:149], off offset:3072
	s_nop 0
	v_addc_co_u32_e32 v181, vcc, 0, v127, vcc
	global_load_dwordx4 v[152:155], v[180:181], off
	global_load_dwordx4 v[172:175], v[180:181], off offset:1024
	s_waitcnt vmcnt(9)
	v_mfma_f32_32x32x16_bf16 v[0:15], v[20:23], v[132:135], 0
	global_load_dwordx4 v[176:179], v[180:181], off offset:2048
	global_load_dwordx4 v[184:187], v[180:181], off offset:3072
	s_mov_b32 s4, 0xb000
	v_add_co_u32_e32 v128, vcc, s4, v122
	s_mov_b32 s4, 0xa000
	s_nop 0
	v_addc_co_u32_e32 v129, vcc, 0, v123, vcc
	s_waitcnt vmcnt(10)
	v_mfma_f32_32x32x16_bf16 v[0:15], v[24:27], v[136:139], v[0:15]
	global_load_dwordx4 v[168:171], v[128:129], off offset:-4096
	global_load_dwordx4 v[200:203], v[128:129], off
	v_add_co_u32_e32 v180, vcc, s4, v122
	global_load_dwordx4 v[212:215], v[128:129], off offset:3072
	s_nop 0
	v_addc_co_u32_e32 v181, vcc, 0, v123, vcc
	s_waitcnt vmcnt(11)
	v_mfma_f32_32x32x16_bf16 v[0:15], v[28:31], v[144:147], v[0:15]
	global_load_dwordx4 v[188:191], v[180:181], off offset:1024
	global_load_dwordx4 v[192:195], v[180:181], off offset:2048
	global_load_dwordx4 v[196:199], v[180:181], off offset:3072
	global_load_dwordx4 v[204:207], v[128:129], off offset:1024
	global_load_dwordx4 v[208:211], v[128:129], off offset:2048
	v_or_b32_e32 v128, 10, v115
	v_mad_u64_u32 v[128:129], s[4:5], v128, s92, v[116:117]
	s_waitcnt vmcnt(12)
	v_mfma_f32_32x32x16_bf16 v[0:15], v[16:19], v[148:151], v[0:15]
	v_mad_i32_i24 v129, s7, v236, v129
	v_lshl_add_u64 v[128:129], v[128:129], 0, s[0:1]
	v_lshl_add_u64 v[128:129], v[128:129], 0, v[120:121]
	v_lshl_add_u64 v[128:129], v[128:129], 0, v[118:119]
	v_add_co_u32_e32 v132, vcc, s66, v128
	v_mfma_f32_32x32x16_bf16 v[0:15], v[32:35], v[140:143], v[0:15]
	s_nop 0
	v_addc_co_u32_e32 v133, vcc, 0, v129, vcc
	v_mfma_f32_32x32x16_bf16 v[0:15], v[36:39], v[156:159], v[0:15]
	s_waitcnt vmcnt(11)
	s_waitcnt vmcnt(10)
	s_waitcnt vmcnt(9)
	s_waitcnt vmcnt(8)
	s_waitcnt vmcnt(0)
; __device__ __forceinline__ unsigned f2bf(float f) { return cvtpk(f, 0.f); }
; __device__ __forceinline__ float gelu_tanh(float x) { const float u = 0.7978845608028654f * (x + 0.044715f * x * x * x); const float th = 1.0f - 2.0f * __builtin_amdgcn_rcpf(__expf(2.0f * u) + 1.0f); return 0.5f * x * (1.0f + th); }
; __device__ __forceinline__ int crow16(int g, int hh) { return (g & 3) + 8 * (g >> 2) + 4 * hh; }
; __device__ __forceinline__ void ssm_v2(const KA& A, const Ctx& F, int l, int b, int g) {
;     ...
;           for (int s = 0; s < 16; ++s) if (s <= 2 * nt + 1) acc = __builtin_amdgcn_mfma_f32_32x32x16_bf16(uf[s], tf[s], acc, 0, 0, 0);
; #pragma unroll
;           for (int s = 0; s < 8; ++s) acc = __builtin_amdgcn_mfma_f32_32x32x16_bf16(xf[s], hf[s], acc, 0, 0, 0); }
;         bf16* op = PS + (tok0 + 2 * nt + (r32 >> 4)) * PSW + C_SSM + 16 * g + (r32 & 15);
; #pragma unroll
;         for (int q = 0; q < 16; ++q) { const bf16 gv_ = (bf16)f2bf(gelu_tanh(acc[q])); if (!(F.dry && (DRY_SEL & 2))) op[(size_t)(16 * crow16(q, hh)) * PSW] = gv_; }
	v_mfma_f32_32x32x16_bf16 v[0:15], v[52:55], v[160:163], v[0:15]
	s_mov_b32 s4, 0x19000
	v_mfma_f32_32x32x16_bf16 v[0:15], v[48:51], v[164:167], v[0:15]
	v_mfma_f32_32x32x16_bf16 v[0:15], v[40:43], v[152:155], v[0:15]
	v_mfma_f32_32x32x16_bf16 v[0:15], v[44:47], v[172:175], v[0:15]
	v_mfma_f32_32x32x16_bf16 v[0:15], v[56:59], v[176:179], v[0:15]
	v_mfma_f32_32x32x16_bf16 v[0:15], v[60:63], v[184:187], v[0:15]
	v_mfma_f32_32x32x16_bf16 v[0:15], v[82:85], v[168:171], v[0:15]
	v_mfma_f32_32x32x16_bf16 v[0:15], v[86:89], v[188:191], v[0:15]
	v_mfma_f32_32x32x16_bf16 v[0:15], v[90:93], v[192:195], v[0:15]
	v_mfma_f32_32x32x16_bf16 v[0:15], v[94:97], v[196:199], v[0:15]
	v_mfma_f32_32x32x16_bf16 v[0:15], v[98:101], v[200:203], v[0:15]
	v_mfma_f32_32x32x16_bf16 v[0:15], v[102:105], v[204:207], v[0:15]
	v_mfma_f32_32x32x16_bf16 v[0:15], v[110:113], v[208:211], v[0:15]
	v_mfma_f32_32x32x16_bf16 v[0:15], v[106:109], v[212:215], v[0:15]
	s_nop 11
	v_mul_f32_e32 v80, 0x3d372713, v0
	v_mul_f32_e32 v80, v0, v80
	v_fma_f32 v80, v0, v80, v0
	v_mul_f32_e32 v80, 0x3f4c422a, v80
	v_add_f32_e32 v80, v80, v80
	v_mul_f32_e32 v80, 0x3fb8aa3b, v80
	v_exp_f32_e32 v80, v80
	v_mul_f32_e32 v131, 0x3d372713, v1
	v_mul_f32_e32 v131, v1, v131
	v_fma_f32 v131, v1, v131, v1
	v_add_f32_e32 v80, 1.0, v80
	v_mul_f32_e32 v131, 0x3f4c422a, v131
	v_rcp_f32_e32 v80, v80
	v_add_f32_e32 v131, v131, v131
	v_mul_f32_e32 v131, 0x3fb8aa3b, v131
	v_exp_f32_e32 v131, v131
	v_fma_f32 v80, v80, -2.0, 1.0
	v_mul_f32_e32 v0, 0.5, v0
	v_add_f32_e32 v80, 1.0, v80
	v_mul_f32_e32 v0, v0, v80
	v_add_f32_e32 v80, 1.0, v131
	v_rcp_f32_e32 v80, v80
	v_cvt_pk_bf16_f32 v0, v0, s0
	global_store_short v[132:133], v0, off offset:1024
	v_mul_f32_e32 v1, 0.5, v1
	v_fma_f32 v0, v80, -2.0, 1.0
	v_mul_f32_e32 v80, 0x3d372713, v2
	v_mul_f32_e32 v80, v2, v80
	v_fma_f32 v80, v2, v80, v2
	v_mul_f32_e32 v80, 0x3f4c422a, v80
	v_add_f32_e32 v80, v80, v80
	v_mul_f32_e32 v80, 0x3fb8aa3b, v80
	v_exp_f32_e32 v80, v80
	v_add_f32_e32 v0, 1.0, v0
	v_mul_f32_e32 v0, v1, v0
	v_cvt_pk_bf16_f32 v131, v0, s0
	v_add_f32_e32 v0, 1.0, v80
	v_rcp_f32_e32 v80, v0
	v_add_co_u32_e32 v0, vcc, s10, v128
	s_nop 1
	v_addc_co_u32_e32 v1, vcc, 0, v129, vcc
	global_store_short v[0:1], v131, off offset:1024
	v_mul_f32_e32 v1, 0.5, v2
	v_mul_f32_e32 v2, 0x3d372713, v3
	v_mul_f32_e32 v2, v3, v2
	v_fma_f32 v2, v3, v2, v3
	v_mul_f32_e32 v2, 0x3f4c422a, v2
	v_add_f32_e32 v2, v2, v2
	v_mul_f32_e32 v2, 0x3fb8aa3b, v2
	v_exp_f32_e32 v2, v2
	v_fma_f32 v0, v80, -2.0, 1.0
	v_add_f32_e32 v0, 1.0, v0
	v_mul_f32_e32 v0, v1, v0
	v_cvt_pk_bf16_f32 v80, v0, s0
	v_add_f32_e32 v0, 1.0, v2
	v_rcp_f32_e32 v2, v0
	v_add_co_u32_e32 v0, vcc, s11, v128
	s_nop 1
	v_addc_co_u32_e32 v1, vcc, 0, v129, vcc
	global_store_short v[0:1], v80, off offset:1024
	v_fma_f32 v0, v2, -2.0, 1.0
	v_mul_f32_e32 v2, 0x3d372713, v4
	v_mul_f32_e32 v2, v4, v2
	v_fma_f32 v2, v4, v2, v4
	v_mul_f32_e32 v2, 0x3f4c422a, v2
	v_add_f32_e32 v2, v2, v2
	v_mul_f32_e32 v2, 0x3fb8aa3b, v2
	v_exp_f32_e32 v2, v2
	v_mul_f32_e32 v1, 0.5, v3
	v_add_f32_e32 v0, 1.0, v0
	v_mul_f32_e32 v0, v1, v0
	v_cvt_pk_bf16_f32 v3, v0, s0
	v_add_f32_e32 v0, 1.0, v2
	v_rcp_f32_e32 v2, v0
	v_add_co_u32_e32 v0, vcc, s12, v128
	s_nop 1
	v_addc_co_u32_e32 v1, vcc, 0, v129, vcc
	global_store_short v[0:1], v3, off offset:1024
	v_fma_f32 v0, v2, -2.0, 1.0
	v_mul_f32_e32 v2, 0x3d372713, v5
	v_mul_f32_e32 v2, v5, v2
	v_fma_f32 v2, v5, v2, v5
	v_mul_f32_e32 v2, 0x3f4c422a, v2
	v_add_f32_e32 v2, v2, v2
	v_mul_f32_e32 v2, 0x3fb8aa3b, v2
	v_exp_f32_e32 v2, v2
	v_mul_f32_e32 v1, 0.5, v4
	v_add_f32_e32 v0, 1.0, v0
	v_mul_f32_e32 v0, v1, v0
	v_cvt_pk_bf16_f32 v3, v0, s0
	v_add_f32_e32 v0, 1.0, v2
	v_rcp_f32_e32 v2, v0
	v_add_co_u32_e32 v0, vcc, s13, v128
	s_nop 1
	v_addc_co_u32_e32 v1, vcc, 0, v129, vcc
	global_store_short v[0:1], v3, off offset:1024
	v_fma_f32 v0, v2, -2.0, 1.0
	v_mul_f32_e32 v2, 0x3d372713, v6
	v_mul_f32_e32 v2, v6, v2
	v_fma_f32 v2, v6, v2, v6
	v_mul_f32_e32 v2, 0x3f4c422a, v2
	v_add_f32_e32 v2, v2, v2
	v_mul_f32_e32 v2, 0x3fb8aa3b, v2
	v_exp_f32_e32 v2, v2
	v_mul_f32_e32 v1, 0.5, v5
	v_add_f32_e32 v0, 1.0, v0
	v_mul_f32_e32 v0, v1, v0
	v_cvt_pk_bf16_f32 v3, v0, s0
	v_add_f32_e32 v0, 1.0, v2
	v_rcp_f32_e32 v2, v0
	v_add_co_u32_e32 v0, vcc, s14, v128
	s_nop 1
	v_addc_co_u32_e32 v1, vcc, 0, v129, vcc
	global_store_short v[0:1], v3, off offset:1024
	v_fma_f32 v0, v2, -2.0, 1.0
	v_mul_f32_e32 v2, 0x3d372713, v7
	v_mul_f32_e32 v2, v7, v2
	v_fma_f32 v2, v7, v2, v7
	v_mul_f32_e32 v2, 0x3f4c422a, v2
	v_add_f32_e32 v2, v2, v2
	v_mul_f32_e32 v2, 0x3fb8aa3b, v2
	v_exp_f32_e32 v2, v2
	v_mul_f32_e32 v1, 0.5, v6
	v_add_f32_e32 v0, 1.0, v0
	v_mul_f32_e32 v0, v1, v0
	v_cvt_pk_bf16_f32 v3, v0, s0
	v_add_f32_e32 v0, 1.0, v2
	v_rcp_f32_e32 v2, v0
	v_add_co_u32_e32 v0, vcc, s15, v128
	s_nop 1
	v_addc_co_u32_e32 v1, vcc, 0, v129, vcc
	global_store_short v[0:1], v3, off offset:1024
	v_fma_f32 v0, v2, -2.0, 1.0
	v_mul_f32_e32 v2, 0x3d372713, v8
	v_mul_f32_e32 v2, v8, v2
	v_fma_f32 v2, v8, v2, v8
	v_mul_f32_e32 v2, 0x3f4c422a, v2
	v_add_f32_e32 v2, v2, v2
	v_mul_f32_e32 v2, 0x3fb8aa3b, v2
	v_exp_f32_e32 v2, v2
	v_mul_f32_e32 v1, 0.5, v7
	v_add_f32_e32 v0, 1.0, v0
	v_mul_f32_e32 v0, v1, v0
	v_cvt_pk_bf16_f32 v3, v0, s0
	v_add_f32_e32 v0, 1.0, v2
	v_rcp_f32_e32 v2, v0
	v_add_co_u32_e32 v0, vcc, s16, v128
	s_nop 1
	v_addc_co_u32_e32 v1, vcc, 0, v129, vcc
	global_store_short v[0:1], v3, off offset:1024
	v_fma_f32 v0, v2, -2.0, 1.0
	v_mul_f32_e32 v2, 0x3d372713, v9
	v_mul_f32_e32 v2, v9, v2
	v_fma_f32 v2, v9, v2, v9
	v_mul_f32_e32 v2, 0x3f4c422a, v2
	v_add_f32_e32 v2, v2, v2
	v_mul_f32_e32 v2, 0x3fb8aa3b, v2
	v_exp_f32_e32 v2, v2
; __device__ __forceinline__ unsigned f2bf(float f) { return cvtpk(f, 0.f); }
; __device__ __forceinline__ float gelu_tanh(float x) { const float u = 0.7978845608028654f * (x + 0.044715f * x * x * x); const float th = 1.0f - 2.0f * __builtin_amdgcn_rcpf(__expf(2.0f * u) + 1.0f); return 0.5f * x * (1.0f + th); }
; __device__ __forceinline__ int crow16(int g, int hh) { return (g & 3) + 8 * (g >> 2) + 4 * hh; }
; __device__ __forceinline__ void ssm_v2(const KA& A, const Ctx& F, int l, int b, int g) {
;     ...
;         const bf16* tp = TM + (size_t)(nt * 16 * 64 + lane) * 8; const bf16* hp = HM + (size_t)(nt * 8 * 64 + lane) * 8;
;         { bf16x8_t tf[16], hf[8];
; #pragma unroll
;           for (int s = 0; s < 16; ++s) if (s <= 2 * nt + 1) tf[s] = *(const bf16x8_t*)(tp + s * 512);
; #pragma unroll
;           for (int s = 0; s < 8; ++s) hf[s] = *(const bf16x8_t*)(hp + s * 512);
; #pragma unroll
;           for (int s = 0; s < 16; ++s) if (s <= 2 * nt + 1) asm volatile("" :: "v"(tf[s]));
;           asm volatile("" :: "v"(hf[0]), "v"(hf[1]), "v"(hf[2]), "v"(hf[3]), "v"(hf[4]), "v"(hf[5]), "v"(hf[6]), "v"(hf[7]));
; #pragma unroll
;           for (int s = 0; s < 16; ++s) if (s <= 2 * nt + 1) acc = __builtin_amdgcn_mfma_f32_32x32x16_bf16(uf[s], tf[s], acc, 0, 0, 0);
; #pragma unroll
;           for (int s = 0; s < 8; ++s) acc = __builtin_amdgcn_mfma_f32_32x32x16_bf16(xf[s], hf[s], acc, 0, 0, 0); }
;         bf16* op = PS + (tok0 + 2 * nt + (r32 >> 4)) * PSW + C_SSM + 16 * g + (r32 & 15);
; #pragma unroll
;         for (int q = 0; q < 16; ++q) { const bf16 gv_ = (bf16)f2bf(gelu_tanh(acc[q])); if (!(F.dry && (DRY_SEL & 2))) op[(size_t)(16 * crow16(q, hh)) * PSW] = gv_; }
	v_mul_f32_e32 v1, 0.5, v8
	v_add_f32_e32 v0, 1.0, v0
	v_mul_f32_e32 v0, v1, v0
	v_cvt_pk_bf16_f32 v3, v0, s0
	v_add_f32_e32 v0, 1.0, v2
	v_rcp_f32_e32 v2, v0
	v_add_co_u32_e32 v0, vcc, s17, v128
	s_nop 1
	v_addc_co_u32_e32 v1, vcc, 0, v129, vcc
	global_store_short v[0:1], v3, off offset:1024
	v_fma_f32 v0, v2, -2.0, 1.0
	v_mul_f32_e32 v2, 0x3d372713, v10
	v_mul_f32_e32 v2, v10, v2
	v_fma_f32 v2, v10, v2, v10
	v_mul_f32_e32 v2, 0x3f4c422a, v2
	v_add_f32_e32 v2, v2, v2
	v_mul_f32_e32 v2, 0x3fb8aa3b, v2
	v_exp_f32_e32 v2, v2
	v_mul_f32_e32 v1, 0.5, v9
	v_add_f32_e32 v0, 1.0, v0
	v_mul_f32_e32 v0, v1, v0
	v_cvt_pk_bf16_f32 v3, v0, s0
	v_add_f32_e32 v0, 1.0, v2
	v_rcp_f32_e32 v2, v0
	v_add_co_u32_e32 v0, vcc, s18, v128
	s_nop 1
	v_addc_co_u32_e32 v1, vcc, 0, v129, vcc
	global_store_short v[0:1], v3, off offset:1024
	v_fma_f32 v0, v2, -2.0, 1.0
	v_mul_f32_e32 v2, 0x3d372713, v11
	v_mul_f32_e32 v2, v11, v2
	v_fma_f32 v2, v11, v2, v11
	v_mul_f32_e32 v2, 0x3f4c422a, v2
	v_add_f32_e32 v2, v2, v2
	v_mul_f32_e32 v2, 0x3fb8aa3b, v2
	v_exp_f32_e32 v2, v2
	v_mul_f32_e32 v1, 0.5, v10
	v_add_f32_e32 v0, 1.0, v0
	v_mul_f32_e32 v0, v1, v0
	v_cvt_pk_bf16_f32 v3, v0, s0
	v_add_f32_e32 v0, 1.0, v2
	v_rcp_f32_e32 v2, v0
	v_add_co_u32_e32 v0, vcc, s19, v128
	s_nop 1
	v_addc_co_u32_e32 v1, vcc, 0, v129, vcc
	global_store_short v[0:1], v3, off offset:1024
	v_fma_f32 v0, v2, -2.0, 1.0
	v_mul_f32_e32 v2, 0x3d372713, v12
	v_mul_f32_e32 v2, v12, v2
	v_fma_f32 v2, v12, v2, v12
	v_mul_f32_e32 v2, 0x3f4c422a, v2
	v_add_f32_e32 v2, v2, v2
	v_mul_f32_e32 v2, 0x3fb8aa3b, v2
	v_exp_f32_e32 v2, v2
	v_mul_f32_e32 v1, 0.5, v11
	v_add_f32_e32 v0, 1.0, v0
	v_mul_f32_e32 v0, v1, v0
	v_cvt_pk_bf16_f32 v3, v0, s0
	v_add_f32_e32 v0, 1.0, v2
	v_rcp_f32_e32 v2, v0
	v_add_co_u32_e32 v0, vcc, s20, v128
	s_nop 1
	v_addc_co_u32_e32 v1, vcc, 0, v129, vcc
	global_store_short v[0:1], v3, off offset:1024
	v_fma_f32 v0, v2, -2.0, 1.0
	v_mul_f32_e32 v2, 0x3d372713, v13
	v_mul_f32_e32 v2, v13, v2
	v_fma_f32 v2, v13, v2, v13
	v_mul_f32_e32 v2, 0x3f4c422a, v2
	v_add_f32_e32 v2, v2, v2
	v_mul_f32_e32 v2, 0x3fb8aa3b, v2
	v_exp_f32_e32 v2, v2
	v_mul_f32_e32 v1, 0.5, v12
	v_add_f32_e32 v0, 1.0, v0
	v_mul_f32_e32 v0, v1, v0
	v_cvt_pk_bf16_f32 v3, v0, s0
	v_add_f32_e32 v0, 1.0, v2
	v_rcp_f32_e32 v2, v0
	v_add_co_u32_e32 v0, vcc, s21, v128
	s_nop 1
	v_addc_co_u32_e32 v1, vcc, 0, v129, vcc
	global_store_short v[0:1], v3, off offset:1024
	v_fma_f32 v0, v2, -2.0, 1.0
	v_mul_f32_e32 v2, 0x3d372713, v14
	v_mul_f32_e32 v2, v14, v2
	v_fma_f32 v2, v14, v2, v14
	v_mul_f32_e32 v2, 0x3f4c422a, v2
	v_add_f32_e32 v2, v2, v2
	v_mul_f32_e32 v2, 0x3fb8aa3b, v2
	v_exp_f32_e32 v2, v2
	v_mul_f32_e32 v1, 0.5, v13
	v_add_f32_e32 v0, 1.0, v0
	v_mul_f32_e32 v0, v1, v0
	v_cvt_pk_bf16_f32 v3, v0, s0
	v_add_f32_e32 v0, 1.0, v2
	v_rcp_f32_e32 v2, v0
	v_add_co_u32_e32 v0, vcc, s22, v128
	s_nop 1
	v_addc_co_u32_e32 v1, vcc, 0, v129, vcc
	global_store_short v[0:1], v3, off offset:1024
	v_fma_f32 v0, v2, -2.0, 1.0
	v_mul_f32_e32 v2, 0x3d372713, v15
	v_mul_f32_e32 v2, v15, v2
	v_fma_f32 v2, v15, v2, v15
	v_mul_f32_e32 v2, 0x3f4c422a, v2
	v_add_f32_e32 v2, v2, v2
	v_mul_f32_e32 v2, 0x3fb8aa3b, v2
	v_exp_f32_e32 v2, v2
	v_mul_f32_e32 v1, 0.5, v14
	v_add_f32_e32 v0, 1.0, v0
	v_mul_f32_e32 v0, v1, v0
	v_cvt_pk_bf16_f32 v3, v0, s0
	v_add_f32_e32 v0, 1.0, v2
	v_rcp_f32_e32 v2, v0
	v_add_co_u32_e32 v0, vcc, s23, v128
	s_nop 1
	v_addc_co_u32_e32 v1, vcc, 0, v129, vcc
	global_store_short v[0:1], v3, off offset:1024
	v_fma_f32 v0, v2, -2.0, 1.0
	v_mul_f32_e32 v1, 0.5, v15
	v_add_f32_e32 v0, 1.0, v0
	v_mul_f32_e32 v0, v1, v0
	v_cvt_pk_bf16_f32 v2, v0, s0
	v_add_co_u32_e32 v0, vcc, s30, v128
	s_nop 1
	v_addc_co_u32_e32 v1, vcc, 0, v129, vcc
	v_add_co_u32_e32 v128, vcc, s4, v126
	global_store_short v[0:1], v2, off offset:1024
	s_nop 0
	v_addc_co_u32_e32 v129, vcc, 0, v127, vcc
	global_load_dwordx4 v[132:135], v[128:129], off offset:-4096
	s_mov_b32 s4, 0x18000
	v_add_co_u32_e32 v148, vcc, s4, v126
	s_mov_b32 s4, 0x1a000
	s_nop 0
	v_addc_co_u32_e32 v149, vcc, 0, v127, vcc
	global_load_dwordx4 v[136:139], v[148:149], off offset:1024
	global_load_dwordx4 v[140:143], v[128:129], off
	global_load_dwordx4 v[144:147], v[148:149], off offset:2048
	global_load_dwordx4 v[164:167], v[128:129], off offset:3072
	global_load_dwordx4 v[156:159], v[128:129], off offset:1024
	global_load_dwordx4 v[160:163], v[128:129], off offset:2048
	v_add_co_u32_e32 v176, vcc, s4, v126
	global_load_dwordx4 v[148:151], v[148:149], off offset:3072
	s_nop 0
	v_addc_co_u32_e32 v177, vcc, 0, v127, vcc
	s_mov_b32 s4, 0x1b000
	v_add_co_u32_e32 v128, vcc, s4, v126
	global_load_dwordx4 v[152:155], v[176:177], off offset:1024
	s_nop 0
	v_addc_co_u32_e32 v129, vcc, 0, v127, vcc
	global_load_dwordx4 v[168:171], v[128:129], off offset:-4096
	s_waitcnt vmcnt(9)
	v_mfma_f32_32x32x16_bf16 v[0:15], v[20:23], v[132:135], 0
	global_load_dwordx4 v[172:175], v[176:177], off offset:2048
	global_load_dwordx4 v[184:187], v[128:129], off
	global_load_dwordx4 v[188:191], v[128:129], off offset:1024
	global_load_dwordx4 v[192:195], v124, s[2:3]
	global_load_dwordx4 v[196:199], v124, s[2:3] offset:1024
	global_load_dwordx4 v[200:203], v124, s[2:3] offset:2048
	global_load_dwordx4 v[204:207], v124, s[2:3] offset:3072
	s_waitcnt vmcnt(15)
	v_mfma_f32_32x32x16_bf16 v[0:15], v[24:27], v[136:139], v[0:15]
	global_load_dwordx4 v[176:179], v[176:177], off offset:3072
	v_lshl_add_u64 v[124:125], s[2:3], 0, v[124:125]
	v_add_co_u32_e32 v124, vcc, s66, v124
	s_nop 1
	v_addc_co_u32_e32 v125, vcc, 0, v125, vcc
	s_waitcnt vmcnt(14)
; __device__ __forceinline__ unsigned f2bf(float f) { return cvtpk(f, 0.f); }
; __device__ __forceinline__ float gelu_tanh(float x) { const float u = 0.7978845608028654f * (x + 0.044715f * x * x * x); const float th = 1.0f - 2.0f * __builtin_amdgcn_rcpf(__expf(2.0f * u) + 1.0f); return 0.5f * x * (1.0f + th); }
; __device__ __forceinline__ int crow16(int g, int hh) { return (g & 3) + 8 * (g >> 2) + 4 * hh; }
; __device__ __forceinline__ void ssm_v2(const KA& A, const Ctx& F, int l, int b, int g) {
;     ...
;           for (int s = 0; s < 16; ++s) if (s <= 2 * nt + 1) tf[s] = *(const bf16x8_t*)(tp + s * 512);
; #pragma unroll
;           for (int s = 0; s < 8; ++s) hf[s] = *(const bf16x8_t*)(hp + s * 512);
; #pragma unroll
;           for (int s = 0; s < 16; ++s) if (s <= 2 * nt + 1) asm volatile("" :: "v"(tf[s]));
;           asm volatile("" :: "v"(hf[0]), "v"(hf[1]), "v"(hf[2]), "v"(hf[3]), "v"(hf[4]), "v"(hf[5]), "v"(hf[6]), "v"(hf[7]));
; #pragma unroll
;           for (int s = 0; s < 16; ++s) if (s <= 2 * nt + 1) acc = __builtin_amdgcn_mfma_f32_32x32x16_bf16(uf[s], tf[s], acc, 0, 0, 0);
; #pragma unroll
;           for (int s = 0; s < 8; ++s) acc = __builtin_amdgcn_mfma_f32_32x32x16_bf16(xf[s], hf[s], acc, 0, 0, 0); }
;         bf16* op = PS + (tok0 + 2 * nt + (r32 >> 4)) * PSW + C_SSM + 16 * g + (r32 & 15);
; #pragma unroll
;         for (int q = 0; q < 16; ++q) { const bf16 gv_ = (bf16)f2bf(gelu_tanh(acc[q])); if (!(F.dry && (DRY_SEL & 2))) op[(size_t)(16 * crow16(q, hh)) * PSW] = gv_; }
	v_mfma_f32_32x32x16_bf16 v[0:15], v[28:31], v[144:147], v[0:15]
	global_load_dwordx4 v[208:211], v[124:125], off
	global_load_dwordx4 v[212:215], v[124:125], off offset:1024
	global_load_dwordx4 v[216:219], v[124:125], off offset:2048
	global_load_dwordx4 v[244:247], v[124:125], off offset:3072
	v_or_b32_e32 v124, 12, v115
	v_mad_u64_u32 v[124:125], s[2:3], v124, s92, v[116:117]
	v_mad_i32_i24 v125, s7, v236, v125
	s_waitcnt vmcnt(14)
	v_mfma_f32_32x32x16_bf16 v[0:15], v[16:19], v[148:151], v[0:15]
	v_lshl_add_u64 v[124:125], v[124:125], 0, s[0:1]
	v_lshl_add_u64 v[124:125], v[124:125], 0, v[120:121]
	v_lshl_add_u64 v[124:125], v[124:125], 0, v[118:119]
	v_mfma_f32_32x32x16_bf16 v[0:15], v[32:35], v[140:143], v[0:15]
	s_waitcnt vmcnt(12)
	s_waitcnt vmcnt(11)
	v_mfma_f32_32x32x16_bf16 v[0:15], v[36:39], v[156:159], v[0:15]
	s_waitcnt vmcnt(4)
	s_waitcnt vmcnt(0)
	v_mfma_f32_32x32x16_bf16 v[0:15], v[52:55], v[160:163], v[0:15]
	s_mov_b32 s2, 0x1d000
	v_mfma_f32_32x32x16_bf16 v[0:15], v[48:51], v[164:167], v[0:15]
	v_mfma_f32_32x32x16_bf16 v[0:15], v[40:43], v[168:171], v[0:15]
	v_mfma_f32_32x32x16_bf16 v[0:15], v[44:47], v[152:155], v[0:15]
	v_mfma_f32_32x32x16_bf16 v[0:15], v[56:59], v[172:175], v[0:15]
	v_mfma_f32_32x32x16_bf16 v[0:15], v[60:63], v[176:179], v[0:15]
	v_mfma_f32_32x32x16_bf16 v[0:15], v[64:67], v[184:187], v[0:15]
	v_mfma_f32_32x32x16_bf16 v[0:15], v[68:71], v[188:191], v[0:15]
	v_mfma_f32_32x32x16_bf16 v[0:15], v[82:85], v[192:195], v[0:15]
	v_mfma_f32_32x32x16_bf16 v[0:15], v[86:89], v[196:199], v[0:15]
	v_mfma_f32_32x32x16_bf16 v[0:15], v[90:93], v[200:203], v[0:15]
	v_mfma_f32_32x32x16_bf16 v[0:15], v[94:97], v[204:207], v[0:15]
	v_mfma_f32_32x32x16_bf16 v[0:15], v[98:101], v[208:211], v[0:15]
	v_mfma_f32_32x32x16_bf16 v[0:15], v[102:105], v[212:215], v[0:15]
	v_mfma_f32_32x32x16_bf16 v[0:15], v[110:113], v[216:219], v[0:15]
	v_mfma_f32_32x32x16_bf16 v[0:15], v[106:109], v[244:247], v[0:15]
	s_nop 11
	v_mul_f32_e32 v80, 0x3d372713, v0
	v_mul_f32_e32 v80, v0, v80
	v_fma_f32 v80, v0, v80, v0
	v_mul_f32_e32 v80, 0x3f4c422a, v80
	v_add_f32_e32 v80, v80, v80
	v_mul_f32_e32 v80, 0x3fb8aa3b, v80
	v_exp_f32_e32 v80, v80
	v_mul_f32_e32 v128, 0x3d372713, v1
	v_mul_f32_e32 v128, v1, v128
	v_fma_f32 v128, v1, v128, v1
	v_add_f32_e32 v80, 1.0, v80
	v_mul_f32_e32 v128, 0x3f4c422a, v128
	v_rcp_f32_e32 v80, v80
	v_add_f32_e32 v128, v128, v128
	v_mul_f32_e32 v128, 0x3fb8aa3b, v128
	v_exp_f32_e32 v128, v128
	v_fma_f32 v80, v80, -2.0, 1.0
	v_mul_f32_e32 v0, 0.5, v0
	v_add_f32_e32 v80, 1.0, v80
	v_mul_f32_e32 v0, v0, v80
	v_add_f32_e32 v80, 1.0, v128
	v_rcp_f32_e32 v80, v80
	v_add_co_u32_e32 v128, vcc, s66, v124
	v_cvt_pk_bf16_f32 v0, v0, s0
	s_nop 0
	v_addc_co_u32_e32 v129, vcc, 0, v125, vcc
	global_store_short v[128:129], v0, off offset:1024
	v_fma_f32 v0, v80, -2.0, 1.0
	v_mul_f32_e32 v80, 0x3d372713, v2
	v_mul_f32_e32 v80, v2, v80
	v_fma_f32 v80, v2, v80, v2
	v_mul_f32_e32 v80, 0x3f4c422a, v80
	v_add_f32_e32 v80, v80, v80
	v_mul_f32_e32 v80, 0x3fb8aa3b, v80
	v_exp_f32_e32 v80, v80
	v_mul_f32_e32 v1, 0.5, v1
	v_add_f32_e32 v0, 1.0, v0
	v_mul_f32_e32 v0, v1, v0
	v_cvt_pk_bf16_f32 v128, v0, s0
	v_add_f32_e32 v0, 1.0, v80
	v_rcp_f32_e32 v80, v0
	v_add_co_u32_e32 v0, vcc, s10, v124
	s_nop 1
	v_addc_co_u32_e32 v1, vcc, 0, v125, vcc
	global_store_short v[0:1], v128, off offset:1024
	v_mul_f32_e32 v1, 0.5, v2
	v_mul_f32_e32 v2, 0x3d372713, v3
	v_mul_f32_e32 v2, v3, v2
	v_fma_f32 v2, v3, v2, v3
	v_mul_f32_e32 v2, 0x3f4c422a, v2
	v_add_f32_e32 v2, v2, v2
	v_mul_f32_e32 v2, 0x3fb8aa3b, v2
	v_exp_f32_e32 v2, v2
	v_fma_f32 v0, v80, -2.0, 1.0
	v_add_f32_e32 v0, 1.0, v0
	v_mul_f32_e32 v0, v1, v0
	v_cvt_pk_bf16_f32 v80, v0, s0
	v_add_f32_e32 v0, 1.0, v2
	v_rcp_f32_e32 v2, v0
	v_add_co_u32_e32 v0, vcc, s11, v124
	s_nop 1
	v_addc_co_u32_e32 v1, vcc, 0, v125, vcc
	global_store_short v[0:1], v80, off offset:1024
	v_fma_f32 v0, v2, -2.0, 1.0
	v_mul_f32_e32 v2, 0x3d372713, v4
	v_mul_f32_e32 v2, v4, v2
	v_fma_f32 v2, v4, v2, v4
	v_mul_f32_e32 v2, 0x3f4c422a, v2
	v_add_f32_e32 v2, v2, v2
	v_mul_f32_e32 v2, 0x3fb8aa3b, v2
	v_exp_f32_e32 v2, v2
	v_mul_f32_e32 v1, 0.5, v3
	v_add_f32_e32 v0, 1.0, v0
	v_mul_f32_e32 v0, v1, v0
	v_cvt_pk_bf16_f32 v3, v0, s0
	v_add_f32_e32 v0, 1.0, v2
	v_rcp_f32_e32 v2, v0
	v_add_co_u32_e32 v0, vcc, s12, v124
	s_nop 1
	v_addc_co_u32_e32 v1, vcc, 0, v125, vcc
	global_store_short v[0:1], v3, off offset:1024
	v_fma_f32 v0, v2, -2.0, 1.0
	v_mul_f32_e32 v2, 0x3d372713, v5
	v_mul_f32_e32 v2, v5, v2
	v_fma_f32 v2, v5, v2, v5
	v_mul_f32_e32 v2, 0x3f4c422a, v2
	v_add_f32_e32 v2, v2, v2
	v_mul_f32_e32 v2, 0x3fb8aa3b, v2
	v_exp_f32_e32 v2, v2
	v_mul_f32_e32 v1, 0.5, v4
	v_add_f32_e32 v0, 1.0, v0
	v_mul_f32_e32 v0, v1, v0
	v_cvt_pk_bf16_f32 v3, v0, s0
	v_add_f32_e32 v0, 1.0, v2
	v_rcp_f32_e32 v2, v0
	v_add_co_u32_e32 v0, vcc, s13, v124
	s_nop 1
	v_addc_co_u32_e32 v1, vcc, 0, v125, vcc
	global_store_short v[0:1], v3, off offset:1024
	v_fma_f32 v0, v2, -2.0, 1.0
	v_mul_f32_e32 v2, 0x3d372713, v6
	v_mul_f32_e32 v2, v6, v2
	v_fma_f32 v2, v6, v2, v6
	v_mul_f32_e32 v2, 0x3f4c422a, v2
	v_add_f32_e32 v2, v2, v2
	v_mul_f32_e32 v2, 0x3fb8aa3b, v2
	v_exp_f32_e32 v2, v2
	v_mul_f32_e32 v1, 0.5, v5
	v_add_f32_e32 v0, 1.0, v0
	v_mul_f32_e32 v0, v1, v0
	v_cvt_pk_bf16_f32 v3, v0, s0
	v_add_f32_e32 v0, 1.0, v2
	v_rcp_f32_e32 v2, v0
	v_add_co_u32_e32 v0, vcc, s14, v124
	s_nop 1
	v_addc_co_u32_e32 v1, vcc, 0, v125, vcc
	global_store_short v[0:1], v3, off offset:1024
	v_fma_f32 v0, v2, -2.0, 1.0
	v_mul_f32_e32 v2, 0x3d372713, v7
	v_mul_f32_e32 v2, v7, v2
	v_fma_f32 v2, v7, v2, v7
	v_mul_f32_e32 v2, 0x3f4c422a, v2
	v_add_f32_e32 v2, v2, v2
	v_mul_f32_e32 v2, 0x3fb8aa3b, v2
; __device__ __forceinline__ unsigned f2bf(float f) { return cvtpk(f, 0.f); }
; __device__ __forceinline__ float gelu_tanh(float x) { const float u = 0.7978845608028654f * (x + 0.044715f * x * x * x); const float th = 1.0f - 2.0f * __builtin_amdgcn_rcpf(__expf(2.0f * u) + 1.0f); return 0.5f * x * (1.0f + th); }
; __device__ __forceinline__ int crow16(int g, int hh) { return (g & 3) + 8 * (g >> 2) + 4 * hh; }
; __device__ __forceinline__ void ssm_v2(const KA& A, const Ctx& F, int l, int b, int g) {
;     ...
;         const bf16* tp = TM + (size_t)(nt * 16 * 64 + lane) * 8; const bf16* hp = HM + (size_t)(nt * 8 * 64 + lane) * 8;
;         { bf16x8_t tf[16], hf[8];
; #pragma unroll
;           for (int s = 0; s < 16; ++s) if (s <= 2 * nt + 1) tf[s] = *(const bf16x8_t*)(tp + s * 512);
; #pragma unroll
;           for (int s = 0; s < 8; ++s) hf[s] = *(const bf16x8_t*)(hp + s * 512);
; #pragma unroll
;           for (int s = 0; s < 16; ++s) if (s <= 2 * nt + 1) asm volatile("" :: "v"(tf[s]));
;           asm volatile("" :: "v"(hf[0]), "v"(hf[1]), "v"(hf[2]), "v"(hf[3]), "v"(hf[4]), "v"(hf[5]), "v"(hf[6]), "v"(hf[7]));
; #pragma unroll
;           for (int s = 0; s < 16; ++s) if (s <= 2 * nt + 1) acc = __builtin_amdgcn_mfma_f32_32x32x16_bf16(uf[s], tf[s], acc, 0, 0, 0);
; #pragma unroll
;           for (int s = 0; s < 8; ++s) acc = __builtin_amdgcn_mfma_f32_32x32x16_bf16(xf[s], hf[s], acc, 0, 0, 0); }
;         bf16* op = PS + (tok0 + 2 * nt + (r32 >> 4)) * PSW + C_SSM + 16 * g + (r32 & 15);
; #pragma unroll
;         for (int q = 0; q < 16; ++q) { const bf16 gv_ = (bf16)f2bf(gelu_tanh(acc[q])); if (!(F.dry && (DRY_SEL & 2))) op[(size_t)(16 * crow16(q, hh)) * PSW] = gv_; }
	v_exp_f32_e32 v2, v2
	v_mul_f32_e32 v1, 0.5, v6
	v_add_f32_e32 v0, 1.0, v0
	v_mul_f32_e32 v0, v1, v0
	v_cvt_pk_bf16_f32 v3, v0, s0
	v_add_f32_e32 v0, 1.0, v2
	v_rcp_f32_e32 v2, v0
	v_add_co_u32_e32 v0, vcc, s15, v124
	s_nop 1
	v_addc_co_u32_e32 v1, vcc, 0, v125, vcc
	global_store_short v[0:1], v3, off offset:1024
	v_fma_f32 v0, v2, -2.0, 1.0
	v_mul_f32_e32 v2, 0x3d372713, v8
	v_mul_f32_e32 v2, v8, v2
	v_fma_f32 v2, v8, v2, v8
	v_mul_f32_e32 v2, 0x3f4c422a, v2
	v_add_f32_e32 v2, v2, v2
	v_mul_f32_e32 v2, 0x3fb8aa3b, v2
	v_exp_f32_e32 v2, v2
	v_mul_f32_e32 v1, 0.5, v7
	v_add_f32_e32 v0, 1.0, v0
	v_mul_f32_e32 v0, v1, v0
	v_cvt_pk_bf16_f32 v3, v0, s0
	v_add_f32_e32 v0, 1.0, v2
	v_rcp_f32_e32 v2, v0
	v_add_co_u32_e32 v0, vcc, s16, v124
	s_nop 1
	v_addc_co_u32_e32 v1, vcc, 0, v125, vcc
	global_store_short v[0:1], v3, off offset:1024
	v_fma_f32 v0, v2, -2.0, 1.0
	v_mul_f32_e32 v2, 0x3d372713, v9
	v_mul_f32_e32 v2, v9, v2
	v_fma_f32 v2, v9, v2, v9
	v_mul_f32_e32 v2, 0x3f4c422a, v2
	v_add_f32_e32 v2, v2, v2
	v_mul_f32_e32 v2, 0x3fb8aa3b, v2
	v_exp_f32_e32 v2, v2
	v_mul_f32_e32 v1, 0.5, v8
	v_add_f32_e32 v0, 1.0, v0
	v_mul_f32_e32 v0, v1, v0
	v_cvt_pk_bf16_f32 v3, v0, s0
	v_add_f32_e32 v0, 1.0, v2
	v_rcp_f32_e32 v2, v0
	v_add_co_u32_e32 v0, vcc, s17, v124
	s_nop 1
	v_addc_co_u32_e32 v1, vcc, 0, v125, vcc
	global_store_short v[0:1], v3, off offset:1024
	v_fma_f32 v0, v2, -2.0, 1.0
	v_mul_f32_e32 v2, 0x3d372713, v10
	v_mul_f32_e32 v2, v10, v2
	v_fma_f32 v2, v10, v2, v10
	v_mul_f32_e32 v2, 0x3f4c422a, v2
	v_add_f32_e32 v2, v2, v2
	v_mul_f32_e32 v2, 0x3fb8aa3b, v2
	v_exp_f32_e32 v2, v2
	v_mul_f32_e32 v1, 0.5, v9
	v_add_f32_e32 v0, 1.0, v0
	v_mul_f32_e32 v0, v1, v0
	v_cvt_pk_bf16_f32 v3, v0, s0
	v_add_f32_e32 v0, 1.0, v2
	v_rcp_f32_e32 v2, v0
	v_add_co_u32_e32 v0, vcc, s18, v124
	s_nop 1
	v_addc_co_u32_e32 v1, vcc, 0, v125, vcc
	global_store_short v[0:1], v3, off offset:1024
	v_fma_f32 v0, v2, -2.0, 1.0
	v_mul_f32_e32 v2, 0x3d372713, v11
	v_mul_f32_e32 v2, v11, v2
	v_fma_f32 v2, v11, v2, v11
	v_mul_f32_e32 v2, 0x3f4c422a, v2
	v_add_f32_e32 v2, v2, v2
	v_mul_f32_e32 v2, 0x3fb8aa3b, v2
	v_exp_f32_e32 v2, v2
	v_mul_f32_e32 v1, 0.5, v10
	v_add_f32_e32 v0, 1.0, v0
	v_mul_f32_e32 v0, v1, v0
	v_cvt_pk_bf16_f32 v3, v0, s0
	v_add_f32_e32 v0, 1.0, v2
	v_rcp_f32_e32 v2, v0
	v_add_co_u32_e32 v0, vcc, s19, v124
	s_nop 1
	v_addc_co_u32_e32 v1, vcc, 0, v125, vcc
	global_store_short v[0:1], v3, off offset:1024
	v_fma_f32 v0, v2, -2.0, 1.0
	v_mul_f32_e32 v2, 0x3d372713, v12
	v_mul_f32_e32 v2, v12, v2
	v_fma_f32 v2, v12, v2, v12
	v_mul_f32_e32 v2, 0x3f4c422a, v2
	v_add_f32_e32 v2, v2, v2
	v_mul_f32_e32 v2, 0x3fb8aa3b, v2
	v_exp_f32_e32 v2, v2
	v_mul_f32_e32 v1, 0.5, v11
	v_add_f32_e32 v0, 1.0, v0
	v_mul_f32_e32 v0, v1, v0
	v_cvt_pk_bf16_f32 v3, v0, s0
	v_add_f32_e32 v0, 1.0, v2
	v_rcp_f32_e32 v2, v0
	v_add_co_u32_e32 v0, vcc, s20, v124
	s_nop 1
	v_addc_co_u32_e32 v1, vcc, 0, v125, vcc
	global_store_short v[0:1], v3, off offset:1024
	v_fma_f32 v0, v2, -2.0, 1.0
	v_mul_f32_e32 v2, 0x3d372713, v13
	v_mul_f32_e32 v2, v13, v2
	v_fma_f32 v2, v13, v2, v13
	v_mul_f32_e32 v2, 0x3f4c422a, v2
	v_add_f32_e32 v2, v2, v2
	v_mul_f32_e32 v2, 0x3fb8aa3b, v2
	v_exp_f32_e32 v2, v2
	v_mul_f32_e32 v1, 0.5, v12
	v_add_f32_e32 v0, 1.0, v0
	v_mul_f32_e32 v0, v1, v0
	v_cvt_pk_bf16_f32 v3, v0, s0
	v_add_f32_e32 v0, 1.0, v2
	v_rcp_f32_e32 v2, v0
	v_add_co_u32_e32 v0, vcc, s21, v124
	s_nop 1
	v_addc_co_u32_e32 v1, vcc, 0, v125, vcc
	global_store_short v[0:1], v3, off offset:1024
	v_fma_f32 v0, v2, -2.0, 1.0
	v_mul_f32_e32 v2, 0x3d372713, v14
	v_mul_f32_e32 v2, v14, v2
	v_fma_f32 v2, v14, v2, v14
	v_mul_f32_e32 v2, 0x3f4c422a, v2
	v_add_f32_e32 v2, v2, v2
	v_mul_f32_e32 v2, 0x3fb8aa3b, v2
	v_exp_f32_e32 v2, v2
	v_mul_f32_e32 v1, 0.5, v13
	v_add_f32_e32 v0, 1.0, v0
	v_mul_f32_e32 v0, v1, v0
	v_cvt_pk_bf16_f32 v3, v0, s0
	v_add_f32_e32 v0, 1.0, v2
	v_rcp_f32_e32 v2, v0
	v_add_co_u32_e32 v0, vcc, s22, v124
	s_nop 1
	v_addc_co_u32_e32 v1, vcc, 0, v125, vcc
	global_store_short v[0:1], v3, off offset:1024
	v_fma_f32 v0, v2, -2.0, 1.0
	v_mul_f32_e32 v2, 0x3d372713, v15
	v_mul_f32_e32 v2, v15, v2
	v_fma_f32 v2, v15, v2, v15
	v_mul_f32_e32 v2, 0x3f4c422a, v2
	v_add_f32_e32 v2, v2, v2
	v_mul_f32_e32 v2, 0x3fb8aa3b, v2
	v_exp_f32_e32 v2, v2
	v_mul_f32_e32 v1, 0.5, v14
	v_add_f32_e32 v0, 1.0, v0
	v_mul_f32_e32 v0, v1, v0
	v_cvt_pk_bf16_f32 v3, v0, s0
	v_add_f32_e32 v0, 1.0, v2
	v_rcp_f32_e32 v2, v0
	v_add_co_u32_e32 v0, vcc, s23, v124
	s_nop 1
	v_addc_co_u32_e32 v1, vcc, 0, v125, vcc
	global_store_short v[0:1], v3, off offset:1024
	v_fma_f32 v0, v2, -2.0, 1.0
	v_mul_f32_e32 v1, 0.5, v15
	v_add_f32_e32 v0, 1.0, v0
	v_mul_f32_e32 v0, v1, v0
	v_cvt_pk_bf16_f32 v2, v0, s0
	v_add_co_u32_e32 v0, vcc, s30, v124
	s_nop 1
	v_addc_co_u32_e32 v1, vcc, 0, v125, vcc
	v_add_co_u32_e32 v124, vcc, s2, v126
	global_store_short v[0:1], v2, off offset:1024
	s_nop 0
	v_addc_co_u32_e32 v125, vcc, 0, v127, vcc
	global_load_dwordx4 v[132:135], v[124:125], off offset:-4096
	s_mov_b32 s2, 0x1c000
	v_add_co_u32_e32 v128, vcc, s2, v126
	s_mov_b32 s2, 0xe000
	s_nop 0
	v_addc_co_u32_e32 v129, vcc, 0, v127, vcc
	global_load_dwordx4 v[136:139], v[128:129], off offset:1024
	s_waitcnt vmcnt(1)
	v_mfma_f32_32x32x16_bf16 v[0:15], v[20:23], v[132:135], 0
	global_load_dwordx4 v[20:23], v[128:129], off offset:2048
	v_add_co_u32_e32 v148, vcc, s2, v122
	s_mov_b32 s2, 0x1e000
	s_nop 0
	v_addc_co_u32_e32 v149, vcc, 0, v123, vcc
	global_load_dwordx4 v[140:143], v[148:149], off offset:3072
	s_waitcnt vmcnt(2)
; __device__ __forceinline__ unsigned f2bf(float f) { return cvtpk(f, 0.f); }
; __device__ __forceinline__ float gelu_tanh(float x) { const float u = 0.7978845608028654f * (x + 0.044715f * x * x * x); const float th = 1.0f - 2.0f * __builtin_amdgcn_rcpf(__expf(2.0f * u) + 1.0f); return 0.5f * x * (1.0f + th); }
; __device__ __forceinline__ int crow16(int g, int hh) { return (g & 3) + 8 * (g >> 2) + 4 * hh; }
; __device__ __forceinline__ void ssm_v2(const KA& A, const Ctx& F, int l, int b, int g) {
;     ...
;           for (int s = 0; s < 16; ++s) if (s <= 2 * nt + 1) tf[s] = *(const bf16x8_t*)(tp + s * 512);
; #pragma unroll
;           for (int s = 0; s < 8; ++s) hf[s] = *(const bf16x8_t*)(hp + s * 512);
; #pragma unroll
;           for (int s = 0; s < 16; ++s) if (s <= 2 * nt + 1) asm volatile("" :: "v"(tf[s]));
;           asm volatile("" :: "v"(hf[0]), "v"(hf[1]), "v"(hf[2]), "v"(hf[3]), "v"(hf[4]), "v"(hf[5]), "v"(hf[6]), "v"(hf[7]));
; #pragma unroll
;           for (int s = 0; s < 16; ++s) if (s <= 2 * nt + 1) acc = __builtin_amdgcn_mfma_f32_32x32x16_bf16(uf[s], tf[s], acc, 0, 0, 0);
; #pragma unroll
;           for (int s = 0; s < 8; ++s) acc = __builtin_amdgcn_mfma_f32_32x32x16_bf16(xf[s], hf[s], acc, 0, 0, 0); }
;         bf16* op = PS + (tok0 + 2 * nt + (r32 >> 4)) * PSW + C_SSM + 16 * g + (r32 & 15);
; #pragma unroll
;         for (int q = 0; q < 16; ++q) { const bf16 gv_ = (bf16)f2bf(gelu_tanh(acc[q])); if (!(F.dry && (DRY_SEL & 2))) op[(size_t)(16 * crow16(q, hh)) * PSW] = gv_; }
	v_mfma_f32_32x32x16_bf16 v[0:15], v[24:27], v[136:139], v[0:15]
	global_load_dwordx4 v[24:27], v[128:129], off offset:3072
	v_add_co_u32_e32 v128, vcc, s2, v126
	s_mov_b32 s2, 0x1f000
	s_nop 0
	v_addc_co_u32_e32 v129, vcc, 0, v127, vcc
	global_load_dwordx4 v[144:147], v[128:129], off offset:1024
	s_waitcnt vmcnt(3)
	v_mfma_f32_32x32x16_bf16 v[0:15], v[28:31], v[20:23], v[0:15]
	global_load_dwordx4 v[28:31], v[124:125], off
	s_waitcnt vmcnt(2)
	v_mfma_f32_32x32x16_bf16 v[0:15], v[16:19], v[24:27], v[0:15]
	global_load_dwordx4 v[16:19], v[124:125], off offset:1024
	s_waitcnt vmcnt(1)
	v_mfma_f32_32x32x16_bf16 v[0:15], v[32:35], v[28:31], v[0:15]
	global_load_dwordx4 v[32:35], v[124:125], off offset:2048
	s_waitcnt vmcnt(1)
	v_mfma_f32_32x32x16_bf16 v[0:15], v[36:39], v[16:19], v[0:15]
	global_load_dwordx4 v[36:39], v[124:125], off offset:3072
	v_add_co_u32_e32 v124, vcc, s2, v126
	s_mov_b32 s2, 0xf000
	s_nop 0
	v_addc_co_u32_e32 v125, vcc, 0, v127, vcc
	v_add_co_u32_e32 v122, vcc, s2, v122
	s_waitcnt vmcnt(1)
	v_mfma_f32_32x32x16_bf16 v[0:15], v[52:55], v[32:35], v[0:15]
	v_addc_co_u32_e32 v123, vcc, 0, v123, vcc
	s_waitcnt vmcnt(0)
	v_mfma_f32_32x32x16_bf16 v[0:15], v[48:51], v[36:39], v[0:15]
	global_load_dwordx4 v[48:51], v[124:125], off offset:-4096
	global_load_dwordx4 v[52:55], v[124:125], off
	s_waitcnt vmcnt(1)
	v_mfma_f32_32x32x16_bf16 v[0:15], v[40:43], v[48:51], v[0:15]
	global_load_dwordx4 v[40:43], v[128:129], off offset:2048
	v_mfma_f32_32x32x16_bf16 v[0:15], v[44:47], v[144:147], v[0:15]
	global_load_dwordx4 v[44:47], v[128:129], off offset:3072
	s_waitcnt vmcnt(1)
	v_mfma_f32_32x32x16_bf16 v[0:15], v[56:59], v[40:43], v[0:15]
	global_load_dwordx4 v[56:59], v[124:125], off offset:1024
	s_waitcnt vmcnt(1)
	v_mfma_f32_32x32x16_bf16 v[0:15], v[60:63], v[44:47], v[0:15]
	global_load_dwordx4 v[60:63], v[124:125], off offset:2048
	v_mfma_f32_32x32x16_bf16 v[0:15], v[64:67], v[52:55], v[0:15]
	global_load_dwordx4 v[64:67], v[124:125], off offset:3072
	s_waitcnt vmcnt(2)
	v_mfma_f32_32x32x16_bf16 v[0:15], v[68:71], v[56:59], v[0:15]
	global_load_dwordx4 v[68:71], v[122:123], off offset:-4096
	s_waitcnt vmcnt(2)
	v_mfma_f32_32x32x16_bf16 v[0:15], v[76:79], v[60:63], v[0:15]
	global_load_dwordx4 v[76:79], v[148:149], off offset:2048
	s_waitcnt vmcnt(2)
	v_mfma_f32_32x32x16_bf16 v[0:15], v[72:75], v[64:67], v[0:15]
	global_load_dwordx4 v[72:75], v[148:149], off offset:1024
	s_waitcnt vmcnt(2)
	v_mfma_f32_32x32x16_bf16 v[0:15], v[82:85], v[68:71], v[0:15]
	global_load_dwordx4 v[82:85], v[122:123], off
	s_waitcnt vmcnt(1)
	v_mfma_f32_32x32x16_bf16 v[0:15], v[86:89], v[72:75], v[0:15]
	v_mfma_f32_32x32x16_bf16 v[0:15], v[90:93], v[76:79], v[0:15]
	global_load_dwordx4 v[86:89], v[122:123], off offset:1024
	global_load_dwordx4 v[90:93], v[122:123], off offset:2048
	v_mfma_f32_32x32x16_bf16 v[0:15], v[94:97], v[140:143], v[0:15]
	global_load_dwordx4 v[94:97], v[122:123], off offset:3072
	s_waitcnt vmcnt(3)
	v_mfma_f32_32x32x16_bf16 v[0:15], v[98:101], v[82:85], v[0:15]
	s_waitcnt vmcnt(2)
	v_mfma_f32_32x32x16_bf16 v[0:15], v[102:105], v[86:89], v[0:15]
	s_waitcnt vmcnt(0)
	v_mfma_f32_32x32x16_bf16 v[0:15], v[110:113], v[90:93], v[0:15]
	v_mfma_f32_32x32x16_bf16 v[0:15], v[106:109], v[94:97], v[0:15]
	s_nop 11
	v_mul_f32_e32 v16, 0x3d372713, v0
	v_mul_f32_e32 v16, v0, v16
	v_fma_f32 v16, v0, v16, v0
	v_mul_f32_e32 v16, 0x3f4c422a, v16
	v_add_f32_e32 v16, v16, v16
	v_mul_f32_e32 v16, 0x3fb8aa3b, v16
	v_exp_f32_e32 v18, v16
	v_mul_f32_e32 v19, 0x3d372713, v1
	v_mul_f32_e32 v19, v1, v19
	v_fma_f32 v19, v1, v19, v1
	v_add_f32_e32 v18, 1.0, v18
	v_mul_f32_e32 v19, 0x3f4c422a, v19
	v_rcp_f32_e32 v18, v18
	v_add_f32_e32 v19, v19, v19
	v_or_b32_e32 v16, 14, v115
	v_mul_f32_e32 v19, 0x3fb8aa3b, v19
	v_mad_u64_u32 v[16:17], s[2:3], v16, s92, v[116:117]
	v_exp_f32_e32 v19, v19
	v_mad_i32_i24 v17, s7, v236, v17
	v_lshl_add_u64 v[16:17], v[16:17], 0, s[0:1]
	v_fma_f32 v18, v18, -2.0, 1.0
	v_lshl_add_u64 v[16:17], v[16:17], 0, v[120:121]
	v_mul_f32_e32 v0, 0.5, v0
	v_add_f32_e32 v18, 1.0, v18
	v_mul_f32_e32 v0, v0, v18
	v_lshl_add_u64 v[16:17], v[16:17], 0, v[118:119]
	v_add_f32_e32 v18, 1.0, v19
	v_rcp_f32_e32 v20, v18
	v_add_co_u32_e32 v18, vcc, s66, v16
	v_cvt_pk_bf16_f32 v0, v0, s0
	s_nop 0
	v_addc_co_u32_e32 v19, vcc, 0, v17, vcc
	global_store_short v[18:19], v0, off offset:1024
	v_mul_f32_e32 v18, 0x3d372713, v2
	v_mul_f32_e32 v18, v2, v18
	v_fma_f32 v18, v2, v18, v2
	v_mul_f32_e32 v18, 0x3f4c422a, v18
	v_add_f32_e32 v18, v18, v18
	v_mul_f32_e32 v18, 0x3fb8aa3b, v18
	v_exp_f32_e32 v18, v18
	v_fma_f32 v0, v20, -2.0, 1.0
	v_mul_f32_e32 v1, 0.5, v1
	v_add_f32_e32 v0, 1.0, v0
	v_mul_f32_e32 v0, v1, v0
	v_cvt_pk_bf16_f32 v19, v0, s0
	v_add_f32_e32 v0, 1.0, v18
	v_rcp_f32_e32 v18, v0
	v_add_co_u32_e32 v0, vcc, s10, v16
	s_nop 1
	v_addc_co_u32_e32 v1, vcc, 0, v17, vcc
	global_store_short v[0:1], v19, off offset:1024
	v_mul_f32_e32 v1, 0.5, v2
	v_mul_f32_e32 v2, 0x3d372713, v3
	v_mul_f32_e32 v2, v3, v2
	v_fma_f32 v2, v3, v2, v3
	v_mul_f32_e32 v2, 0x3f4c422a, v2
	v_add_f32_e32 v2, v2, v2
	v_mul_f32_e32 v2, 0x3fb8aa3b, v2
	v_exp_f32_e32 v2, v2
	v_fma_f32 v0, v18, -2.0, 1.0
	v_add_f32_e32 v0, 1.0, v0
	v_mul_f32_e32 v0, v1, v0
	v_cvt_pk_bf16_f32 v18, v0, s0
	v_add_f32_e32 v0, 1.0, v2
	v_rcp_f32_e32 v2, v0
	v_add_co_u32_e32 v0, vcc, s11, v16
	s_nop 1
	v_addc_co_u32_e32 v1, vcc, 0, v17, vcc
	global_store_short v[0:1], v18, off offset:1024
	v_fma_f32 v0, v2, -2.0, 1.0
	v_mul_f32_e32 v2, 0x3d372713, v4
	v_mul_f32_e32 v2, v4, v2
	v_fma_f32 v2, v4, v2, v4
	v_mul_f32_e32 v2, 0x3f4c422a, v2
	v_add_f32_e32 v2, v2, v2
	v_mul_f32_e32 v2, 0x3fb8aa3b, v2
	v_exp_f32_e32 v2, v2
; __device__ __forceinline__ unsigned f2bf(float f) { return cvtpk(f, 0.f); }
; __device__ __forceinline__ float gelu_tanh(float x) { const float u = 0.7978845608028654f * (x + 0.044715f * x * x * x); const float th = 1.0f - 2.0f * __builtin_amdgcn_rcpf(__expf(2.0f * u) + 1.0f); return 0.5f * x * (1.0f + th); }
; __device__ __forceinline__ int crow16(int g, int hh) { return (g & 3) + 8 * (g >> 2) + 4 * hh; }
; __device__ __forceinline__ void ssm_v2(const KA& A, const Ctx& F, int l, int b, int g) {
;     ...
;         bf16* op = PS + (tok0 + 2 * nt + (r32 >> 4)) * PSW + C_SSM + 16 * g + (r32 & 15);
; #pragma unroll
;         for (int q = 0; q < 16; ++q) { const bf16 gv_ = (bf16)f2bf(gelu_tanh(acc[q])); if (!(F.dry && (DRY_SEL & 2))) op[(size_t)(16 * crow16(q, hh)) * PSW] = gv_; }
;     }
;     __syncthreads();
	v_mul_f32_e32 v1, 0.5, v3
	v_add_f32_e32 v0, 1.0, v0
	v_mul_f32_e32 v0, v1, v0
	v_cvt_pk_bf16_f32 v3, v0, s0
	v_add_f32_e32 v0, 1.0, v2
	v_rcp_f32_e32 v2, v0
	v_add_co_u32_e32 v0, vcc, s12, v16
	s_nop 1
	v_addc_co_u32_e32 v1, vcc, 0, v17, vcc
	global_store_short v[0:1], v3, off offset:1024
	v_fma_f32 v0, v2, -2.0, 1.0
	v_mul_f32_e32 v2, 0x3d372713, v5
	v_mul_f32_e32 v2, v5, v2
	v_fma_f32 v2, v5, v2, v5
	v_mul_f32_e32 v2, 0x3f4c422a, v2
	v_add_f32_e32 v2, v2, v2
	v_mul_f32_e32 v2, 0x3fb8aa3b, v2
	v_exp_f32_e32 v2, v2
	v_mul_f32_e32 v1, 0.5, v4
	v_add_f32_e32 v0, 1.0, v0
	v_mul_f32_e32 v0, v1, v0
	v_cvt_pk_bf16_f32 v3, v0, s0
	v_add_f32_e32 v0, 1.0, v2
	v_rcp_f32_e32 v2, v0
	v_add_co_u32_e32 v0, vcc, s13, v16
	s_nop 1
	v_addc_co_u32_e32 v1, vcc, 0, v17, vcc
	global_store_short v[0:1], v3, off offset:1024
	v_fma_f32 v0, v2, -2.0, 1.0
	v_mul_f32_e32 v2, 0x3d372713, v6
	v_mul_f32_e32 v2, v6, v2
	v_fma_f32 v2, v6, v2, v6
	v_mul_f32_e32 v2, 0x3f4c422a, v2
	v_add_f32_e32 v2, v2, v2
	v_mul_f32_e32 v2, 0x3fb8aa3b, v2
	v_exp_f32_e32 v2, v2
	v_mul_f32_e32 v1, 0.5, v5
	v_add_f32_e32 v0, 1.0, v0
	v_mul_f32_e32 v0, v1, v0
	v_cvt_pk_bf16_f32 v3, v0, s0
	v_add_f32_e32 v0, 1.0, v2
	v_rcp_f32_e32 v2, v0
	v_add_co_u32_e32 v0, vcc, s14, v16
	s_nop 1
	v_addc_co_u32_e32 v1, vcc, 0, v17, vcc
	global_store_short v[0:1], v3, off offset:1024
	v_fma_f32 v0, v2, -2.0, 1.0
	v_mul_f32_e32 v2, 0x3d372713, v7
	v_mul_f32_e32 v2, v7, v2
	v_fma_f32 v2, v7, v2, v7
	v_mul_f32_e32 v2, 0x3f4c422a, v2
	v_add_f32_e32 v2, v2, v2
	v_mul_f32_e32 v2, 0x3fb8aa3b, v2
	v_exp_f32_e32 v2, v2
	v_mul_f32_e32 v1, 0.5, v6
	v_add_f32_e32 v0, 1.0, v0
	v_mul_f32_e32 v0, v1, v0
	v_cvt_pk_bf16_f32 v3, v0, s0
	v_add_f32_e32 v0, 1.0, v2
	v_rcp_f32_e32 v2, v0
	v_add_co_u32_e32 v0, vcc, s15, v16
	s_nop 1
	v_addc_co_u32_e32 v1, vcc, 0, v17, vcc
	global_store_short v[0:1], v3, off offset:1024
	v_fma_f32 v0, v2, -2.0, 1.0
	v_mul_f32_e32 v2, 0x3d372713, v8
	v_mul_f32_e32 v2, v8, v2
	v_fma_f32 v2, v8, v2, v8
	v_mul_f32_e32 v2, 0x3f4c422a, v2
	v_add_f32_e32 v2, v2, v2
	v_mul_f32_e32 v2, 0x3fb8aa3b, v2
	v_exp_f32_e32 v2, v2
	v_mul_f32_e32 v1, 0.5, v7
	v_add_f32_e32 v0, 1.0, v0
	v_mul_f32_e32 v0, v1, v0
	v_cvt_pk_bf16_f32 v3, v0, s0
	v_add_f32_e32 v0, 1.0, v2
	v_rcp_f32_e32 v2, v0
	v_add_co_u32_e32 v0, vcc, s16, v16
	s_nop 1
	v_addc_co_u32_e32 v1, vcc, 0, v17, vcc
	global_store_short v[0:1], v3, off offset:1024
	v_fma_f32 v0, v2, -2.0, 1.0
	v_mul_f32_e32 v2, 0x3d372713, v9
	v_mul_f32_e32 v2, v9, v2
	v_fma_f32 v2, v9, v2, v9
	v_mul_f32_e32 v2, 0x3f4c422a, v2
	v_add_f32_e32 v2, v2, v2
	v_mul_f32_e32 v2, 0x3fb8aa3b, v2
	v_exp_f32_e32 v2, v2
	v_mul_f32_e32 v1, 0.5, v8
	v_add_f32_e32 v0, 1.0, v0
	v_mul_f32_e32 v0, v1, v0
	v_cvt_pk_bf16_f32 v3, v0, s0
	v_add_f32_e32 v0, 1.0, v2
	v_rcp_f32_e32 v2, v0
	v_add_co_u32_e32 v0, vcc, s17, v16
	s_nop 1
	v_addc_co_u32_e32 v1, vcc, 0, v17, vcc
	global_store_short v[0:1], v3, off offset:1024
	v_fma_f32 v0, v2, -2.0, 1.0
	v_mul_f32_e32 v2, 0x3d372713, v10
	v_mul_f32_e32 v2, v10, v2
	v_fma_f32 v2, v10, v2, v10
	v_mul_f32_e32 v2, 0x3f4c422a, v2
	v_add_f32_e32 v2, v2, v2
	v_mul_f32_e32 v2, 0x3fb8aa3b, v2
	v_exp_f32_e32 v2, v2
	v_mul_f32_e32 v1, 0.5, v9
	v_add_f32_e32 v0, 1.0, v0
	v_mul_f32_e32 v0, v1, v0
	v_cvt_pk_bf16_f32 v3, v0, s0
	v_add_f32_e32 v0, 1.0, v2
	v_rcp_f32_e32 v2, v0
	v_add_co_u32_e32 v0, vcc, s18, v16
	s_nop 1
	v_addc_co_u32_e32 v1, vcc, 0, v17, vcc
	global_store_short v[0:1], v3, off offset:1024
	v_fma_f32 v0, v2, -2.0, 1.0
	v_mul_f32_e32 v2, 0x3d372713, v11
	v_mul_f32_e32 v2, v11, v2
	v_fma_f32 v2, v11, v2, v11
	v_mul_f32_e32 v2, 0x3f4c422a, v2
	v_add_f32_e32 v2, v2, v2
	v_mul_f32_e32 v2, 0x3fb8aa3b, v2
	v_exp_f32_e32 v2, v2
	v_mul_f32_e32 v1, 0.5, v10
	v_add_f32_e32 v0, 1.0, v0
	v_mul_f32_e32 v0, v1, v0
	v_cvt_pk_bf16_f32 v3, v0, s0
	v_add_f32_e32 v0, 1.0, v2
	v_rcp_f32_e32 v2, v0
	v_add_co_u32_e32 v0, vcc, s19, v16
	s_nop 1
	v_addc_co_u32_e32 v1, vcc, 0, v17, vcc
	global_store_short v[0:1], v3, off offset:1024
	v_fma_f32 v0, v2, -2.0, 1.0
	v_mul_f32_e32 v2, 0x3d372713, v12
	v_mul_f32_e32 v2, v12, v2
	v_fma_f32 v2, v12, v2, v12
	v_mul_f32_e32 v2, 0x3f4c422a, v2
	v_add_f32_e32 v2, v2, v2
	v_mul_f32_e32 v2, 0x3fb8aa3b, v2
	v_exp_f32_e32 v2, v2
	v_mul_f32_e32 v1, 0.5, v11
	v_add_f32_e32 v0, 1.0, v0
	v_mul_f32_e32 v0, v1, v0
	v_cvt_pk_bf16_f32 v3, v0, s0
	v_add_f32_e32 v0, 1.0, v2
	v_rcp_f32_e32 v2, v0
	v_add_co_u32_e32 v0, vcc, s20, v16
	s_nop 1
	v_addc_co_u32_e32 v1, vcc, 0, v17, vcc
	global_store_short v[0:1], v3, off offset:1024
	v_fma_f32 v0, v2, -2.0, 1.0
	v_mul_f32_e32 v2, 0x3d372713, v13
	v_mul_f32_e32 v2, v13, v2
	v_fma_f32 v2, v13, v2, v13
	v_mul_f32_e32 v2, 0x3f4c422a, v2
	v_add_f32_e32 v2, v2, v2
	v_mul_f32_e32 v2, 0x3fb8aa3b, v2
	v_exp_f32_e32 v2, v2
	v_mul_f32_e32 v1, 0.5, v12
	v_add_f32_e32 v0, 1.0, v0
	v_mul_f32_e32 v0, v1, v0
	v_cvt_pk_bf16_f32 v3, v0, s0
	v_add_f32_e32 v0, 1.0, v2
	v_rcp_f32_e32 v2, v0
	v_add_co_u32_e32 v0, vcc, s21, v16
	s_nop 1
	v_addc_co_u32_e32 v1, vcc, 0, v17, vcc
	global_store_short v[0:1], v3, off offset:1024
	v_fma_f32 v0, v2, -2.0, 1.0
	v_mul_f32_e32 v2, 0x3d372713, v14
	v_mul_f32_e32 v2, v14, v2
	v_fma_f32 v2, v14, v2, v14
	v_mul_f32_e32 v2, 0x3f4c422a, v2
	v_add_f32_e32 v2, v2, v2
	v_mul_f32_e32 v2, 0x3fb8aa3b, v2
	v_exp_f32_e32 v2, v2
	v_mul_f32_e32 v1, 0.5, v13
	v_add_f32_e32 v0, 1.0, v0
	v_mul_f32_e32 v0, v1, v0
	v_cvt_pk_bf16_f32 v3, v0, s0
	v_add_f32_e32 v0, 1.0, v2
	v_rcp_f32_e32 v2, v0
	v_add_co_u32_e32 v0, vcc, s22, v16
	s_nop 1
	v_addc_co_u32_e32 v1, vcc, 0, v17, vcc
	global_store_short v[0:1], v3, off offset:1024
	v_fma_f32 v0, v2, -2.0, 1.0
	v_mul_f32_e32 v2, 0x3d372713, v15
	v_mul_f32_e32 v2, v15, v2
	v_fma_f32 v2, v15, v2, v15
	v_mul_f32_e32 v2, 0x3f4c422a, v2
	v_add_f32_e32 v2, v2, v2
	v_mul_f32_e32 v2, 0x3fb8aa3b, v2
	v_exp_f32_e32 v2, v2
	v_mul_f32_e32 v1, 0.5, v14
	v_add_f32_e32 v0, 1.0, v0
	v_mul_f32_e32 v0, v1, v0
	v_cvt_pk_bf16_f32 v3, v0, s0
	v_add_f32_e32 v0, 1.0, v2
	v_rcp_f32_e32 v2, v0
	v_add_co_u32_e32 v0, vcc, s23, v16
	s_nop 1
	v_addc_co_u32_e32 v1, vcc, 0, v17, vcc
	global_store_short v[0:1], v3, off offset:1024
	v_fma_f32 v0, v2, -2.0, 1.0
	v_mul_f32_e32 v1, 0.5, v15
	v_add_f32_e32 v0, 1.0, v0
	v_mul_f32_e32 v0, v1, v0
	v_cvt_pk_bf16_f32 v2, v0, s0
	v_add_co_u32_e32 v0, vcc, 0x253000, v16
	s_nop 1
	v_addc_co_u32_e32 v1, vcc, 0, v17, vcc
	global_store_short v[0:1], v2, off offset:1024
	s_barrier
